# early L1 inv in grid barrier for non-leaders; proj+gate-up epilogues: cached row scales, skip first two vmcnt waits after an epilogue
# speedup vs baseline: 1.0125x; 1.0125x over previous
.LBB0_92:
	s_lshl_b32 s6, s29, 8
	s_add_u32 s6, s20, s6
	s_addc_u32 s7, s21, 0
	v_mov_b32_e32 v3, 0x1000
	v_mov_b32_e32 v5, 1
	global_atomic_add v5, v3, v5, s[6:7] offset:1024 sc0
	v_cvt_f32_u32_e32 v3, v4
	v_sub_u32_e32 v6, 0, v4
	v_rcp_iflag_f32_e32 v3, v3
	s_nop 0
	v_mul_f32_e32 v3, 0x4f7ffffe, v3
	v_cvt_u32_f32_e32 v3, v3
	v_mul_lo_u32 v6, v6, v3
	v_mul_hi_u32 v6, v3, v6
	v_add_u32_e32 v3, v3, v6
	s_waitcnt vmcnt(0)
	v_mul_hi_u32 v3, v5, v3
	v_mul_lo_u32 v6, v3, v4
	v_sub_u32_e32 v6, v5, v6
	v_add_u32_e32 v7, 1, v3
	v_cmp_ge_u32_e32 vcc, v6, v4
	v_add_u32_e32 v5, 1, v5
	s_nop 0
	v_cndmask_b32_e32 v3, v3, v7, vcc
	v_sub_u32_e32 v7, v6, v4
	v_cndmask_b32_e32 v6, v6, v7, vcc
	v_add_u32_e32 v7, 1, v3
	v_cmp_ge_u32_e32 vcc, v6, v4
	s_nop 1
	v_cndmask_b32_e32 v3, v3, v7, vcc
	v_mul_lo_u32 v6, v4, v3
	v_add_u32_e32 v4, v6, v4
	v_cmp_ne_u32_e32 vcc, v5, v4
	s_and_saveexec_b64 s[8:9], vcc
	s_xor_b64 s[8:9], exec, s[8:9]
	s_cbranch_execz .LBB0_106
	s_waitcnt lgkmcnt(0)
	v_mov_b32_e32 v2, 0x2000
	buffer_inv sc1
	global_load_dword v2, v2, s[6:7] offset:1024 sc1
	s_add_u32 s14, s6, 0x2400
	s_addc_u32 s15, s7, 0
	s_waitcnt vmcnt(0)
	v_cmp_eq_u32_e32 vcc, v2, v3
	s_and_saveexec_b64 s[10:11], vcc
	s_cbranch_execz .LBB0_105
	s_add_u32 s12, s76, 0x4200
	s_addc_u32 s13, s77, 0
	s_mov_b32 s30, 1
	s_mov_b64 s[16:17], 0
	v_mov_b32_e32 v2, 0
	s_branch .LBB0_96

.LBB0_105:
	s_or_b64 exec, exec, s[10:11]
	s_waitcnt vmcnt(0)
	s_waitcnt vmcnt(0)

.LBB0_295:
	s_lshl_b32 s4, s29, 8
	s_add_u32 s4, s20, s4
	s_addc_u32 s5, s21, 0
	v_mov_b32_e32 v3, 0x1000
	v_mov_b32_e32 v5, 1
	global_atomic_add v5, v3, v5, s[4:5] offset:1024 sc0
	v_cvt_f32_u32_e32 v3, v4
	v_sub_u32_e32 v6, 0, v4
	v_rcp_iflag_f32_e32 v3, v3
	s_nop 0
	v_mul_f32_e32 v3, 0x4f7ffffe, v3
	v_cvt_u32_f32_e32 v3, v3
	v_mul_lo_u32 v6, v6, v3
	v_mul_hi_u32 v6, v3, v6
	v_add_u32_e32 v3, v3, v6
	s_waitcnt vmcnt(0)
	v_mul_hi_u32 v3, v5, v3
	v_mul_lo_u32 v6, v3, v4
	v_sub_u32_e32 v6, v5, v6
	v_add_u32_e32 v7, 1, v3
	v_cmp_ge_u32_e32 vcc, v6, v4
	v_add_u32_e32 v5, 1, v5
	s_nop 0
	v_cndmask_b32_e32 v3, v3, v7, vcc
	v_sub_u32_e32 v7, v6, v4
	v_cndmask_b32_e32 v6, v6, v7, vcc
	v_add_u32_e32 v7, 1, v3
	v_cmp_ge_u32_e32 vcc, v6, v4
	s_nop 1
	v_cndmask_b32_e32 v3, v3, v7, vcc
	v_mul_lo_u32 v6, v4, v3
	v_add_u32_e32 v4, v6, v4
	v_cmp_ne_u32_e32 vcc, v5, v4
	s_and_saveexec_b64 s[6:7], vcc
	s_xor_b64 s[6:7], exec, s[6:7]
	s_cbranch_execz .LBB0_309
	s_waitcnt lgkmcnt(0)
	v_mov_b32_e32 v2, 0x2000
	buffer_inv sc1
	global_load_dword v2, v2, s[4:5] offset:1024 sc1
	s_add_u32 s12, s4, 0x2400
	s_addc_u32 s13, s5, 0
	s_waitcnt vmcnt(0)
	v_cmp_eq_u32_e32 vcc, v2, v3
	s_and_saveexec_b64 s[8:9], vcc
	s_cbranch_execz .LBB0_308
	s_add_u32 s10, s76, 0x4200
	s_addc_u32 s11, s77, 0
	s_mov_b32 s26, 1
	s_mov_b64 s[14:15], 0
	v_mov_b32_e32 v2, 0
	s_branch .LBB0_299

.LBB0_308:
	s_or_b64 exec, exec, s[8:9]
	s_waitcnt vmcnt(0)
	s_waitcnt vmcnt(0)

.LBB0_332:
	s_lshl_b32 s0, s6, 3
	s_or_b32 s2, s0, 3
	v_readlane_b32 s4, v253, 12
	v_readlane_b32 s5, v253, 13
	s_cmp_le_i32 s4, s2
	v_writelane_b32 v254, s0, 58
	s_cselect_b64 s[0:1], -1, 0
	s_cmp_lt_i32 s2, s5
	s_cselect_b64 s[2:3], -1, 0
	s_mov_b32 s7, s73
	s_and_b64 s[0:1], s[0:1], s[2:3]
	v_writelane_b32 v254, s6, 59
	s_andn2_b64 vcc, exec, s[0:1]
	s_nop 0
	v_writelane_b32 v254, s7, 60
	s_cbranch_vccnz .LBB0_349
	s_mov_b64 s[24:25], s[76:77]
	s_load_dword s4, s[58:59], 0x0
	s_mov_b32 s5, s74
	v_mov_b32_e32 v18, v235
	s_waitcnt lgkmcnt(0)
	s_cmpk_gt_i32 s5, 0x6ff
	v_readfirstlane_b32 s18, v18
	s_cbranch_scc1 .LBB0_349
	s_mov_b32 s98, -1
	v_lshlrev_b32_e32 v1, 4, v18
	v_add_u32_e32 v0, 0x2000, v1
	v_ashrrev_i32_e32 v2, 31, v0
	v_lshrrev_b32_e32 v2, 22, v2
	v_add_u32_e32 v2, v0, v2
	v_ashrrev_i32_e32 v12, 10, v2
	v_mul_i32_i24_e32 v2, 0x400, v12
	v_sub_u32_e32 v0, v0, v2
	v_lshrrev_b32_e32 v2, 4, v0
	v_readlane_b32 s6, v254, 59
	v_bitop3_b32 v0, v2, v0, 32 bitop3:0x6c
	v_readlane_b32 s7, v254, 60
	s_mul_hi_u32 s2, s6, 0x1c00000
	s_mul_i32 s3, s6, 0x1c00000
	s_add_u32 s6, s24, 0x22100000
	v_ashrrev_i32_e32 v2, 31, v0
	s_addc_u32 s7, s25, 0
	v_lshrrev_b32_e32 v2, 26, v2
	s_add_u32 s3, s24, s3
	v_add_u32_e32 v2, v0, v2
	v_lshlrev_b32_e32 v4, 3, v12
	s_addc_u32 s2, s25, s2
	v_ashrrev_i32_e32 v13, 6, v2
	v_and_b32_e32 v4, -16, v4
	s_add_u32 s8, s3, 0x900000
	v_add_u32_e32 v4, v13, v4
	s_addc_u32 s9, s2, 0
	v_and_b32_e32 v5, 3, v13
	s_mov_b32 s2, 0xfffe0
	v_lshrrev_b32_e32 v6, 2, v4
	v_lshlrev_b32_e32 v7, 1, v4
	v_and_b32_e32 v2, 0xc0, v2
	v_and_or_b32 v5, v4, s2, v5
	v_and_b32_e32 v6, 4, v6
	v_and_b32_e32 v7, 24, v7
	v_sub_u32_e32 v0, v0, v2
	v_or3_b32 v5, v5, v6, v7
	v_lshlrev_b32_e32 v6, 5, v12
	v_ashrrev_i16_sdwa v0, v233, sext(v0) dst_sel:DWORD dst_unused:UNUSED_PAD src0_sel:DWORD src1_sel:BYTE_0
	v_and_b32_e32 v6, 32, v6
	v_bfe_i32 v14, v0, 0, 16
	v_add_lshl_u32 v2, v6, v14, 1
	v_lshl_add_u32 v0, v5, 12, v2
	v_lshl_add_u32 v132, v4, 12, v2
	v_bfe_i32 v2, v18, 27, 1
	v_lshrrev_b32_e32 v2, 22, v2
	v_add_u32_e32 v2, v1, v2
	v_and_b32_e32 v2, 0xfffffc00, v2
	v_sub_u32_e32 v1, v1, v2
	v_lshrrev_b32_e32 v2, 4, v1
	v_ashrrev_i32_e32 v4, 31, v18
	v_bitop3_b32 v1, v2, v1, 32 bitop3:0x6c
	v_lshrrev_b32_e32 v4, 26, v4
	v_ashrrev_i32_e32 v2, 31, v1
	v_add_u32_e32 v4, v18, v4
	v_lshrrev_b32_e32 v2, 26, v2
	v_ashrrev_i32_e32 v16, 6, v4
	v_add_u32_e32 v2, v1, v2
	v_lshlrev_b32_e32 v4, 3, v16
	v_ashrrev_i32_e32 v15, 6, v2
	v_and_b32_e32 v4, -16, v4
	v_add_u32_e32 v4, v15, v4
	v_and_b32_e32 v5, 3, v15
	s_ashr_i32 s11, s5, 31
	v_and_or_b32 v5, v4, s2, v5
	s_lshr_b32 s2, s11, 29
	s_add_i32 s2, s5, s2
	s_ashr_i32 s16, s18, 6
	s_ashr_i32 s3, s2, 3
	s_and_b32 s2, s2, -8
	s_ashr_i32 s17, s18, 8
	s_lshl_b32 s10, s16, 10
	s_sub_i32 s2, s5, s2
	s_cmp_lt_i32 s2, 0
	s_movk_i32 s12, 0xe1
	s_cselect_b32 s12, s12, 0xe0
	s_mul_i32 s2, s2, s12
	s_add_i32 s2, s2, s3
	s_mul_hi_i32 s3, s2, 0x92492493
	s_add_i32 s3, s3, s2
	s_lshr_b32 s12, s3, 31
	s_ashr_i32 s3, s3, 7
	s_add_i32 s3, s3, s12
	s_lshl_b32 s12, s3, 3
	s_mulk_i32 s3, 0xe0
	s_sub_i32 s2, s2, s3
	s_bfe_u32 s3, s2, 0x3001c
	s_add_i32 s3, s2, s3
	s_sext_i32_i16 s13, s3
	s_and_b32 s3, s3, 0xfff8
	s_sub_i32 s2, s2, s3
	s_sext_i32_i16 s2, s2
	v_lshrrev_b32_e32 v6, 2, v4
	v_lshlrev_b32_e32 v7, 1, v4
	v_and_b32_e32 v2, 0xc0, v2
	s_lshr_b32 s20, s13, 3
	s_add_i32 s42, s12, s2
	v_and_b32_e32 v6, 4, v6
	v_and_b32_e32 v7, 24, v7
	v_sub_u32_e32 v1, v1, v2
	s_ashr_i32 s43, s42, 31
	s_bfe_i64 s[12:13], s[20:21], 0x100000
	v_or3_b32 v5, v5, v6, v7
	v_lshlrev_b32_e32 v6, 5, v16
	v_ashrrev_i16_sdwa v1, v233, sext(v1) dst_sel:DWORD dst_unused:UNUSED_PAD src0_sel:DWORD src1_sel:BYTE_0
	s_lshl_b64 s[2:3], s[42:43], 20
	s_lshl_b64 s[12:13], s[12:13], 20
	v_and_b32_e32 v6, 32, v6
	v_bfe_i32 v17, v1, 0, 16
	s_add_u32 s44, s8, s12
	v_add_lshl_u32 v1, v6, v17, 1
	s_addc_u32 s45, s9, s13
	s_add_i32 s12, s10, 0
	v_lshl_add_u32 v2, v5, 12, v1
	s_add_i32 m0, s12, 0x10000
	v_lshl_add_u32 v134, v4, 12, v1
	global_load_lds_dwordx4 v2, s[44:45]
	s_add_i32 m0, s12, 0x12000
	s_add_u32 s14, s44, 0x80000
	global_load_lds_dwordx4 v0, s[44:45]
	s_addc_u32 s15, s45, 0
	s_add_i32 m0, s12, 0x14000
	v_mov_b32_e32 v1, v3
	global_load_lds_dwordx4 v2, s[14:15]
	s_add_i32 m0, s12, 0x16000
	s_add_u32 s46, s6, s2
	s_addc_u32 s47, s7, s3
	s_add_i32 s13, s12, 0x2000
	global_load_lds_dwordx4 v0, s[14:15]
	s_mov_b32 m0, s12
	s_add_u32 s2, s46, 0x80000
	global_load_lds_dwordx4 v134, s[46:47]
	s_mov_b32 m0, s13
	s_addc_u32 s3, s47, 0
	s_add_i32 s14, s12, 0x4000
	global_load_lds_dwordx4 v132, s[46:47]
	s_mov_b32 m0, s14
	s_add_i32 s15, s12, 0x6000
	global_load_lds_dwordx4 v134, s[2:3]
	s_mov_b32 m0, s15
	v_mov_b32_e32 v135, v3
	global_load_lds_dwordx4 v132, s[2:3]
	v_mov_b32_e32 v133, v3
	s_cmp_eq_u32 s17, 1
	v_lshl_add_u64 v[10:11], s[44:45], 0, v[2:3]
	v_lshl_add_u64 v[8:9], s[44:45], 0, v[0:1]
	v_lshl_add_u64 v[4:5], s[46:47], 0, v[134:135]
	s_cselect_b64 s[2:3], -1, 0
	s_cmp_lg_u32 s17, 1
	v_lshl_add_u64 v[6:7], s[46:47], 0, v[132:133]
	s_cbranch_scc1 .LBB0_336
	s_barrier

.LBB0_339:
	s_add_i32 s19, s19, 1
	s_cmp_gt_u32 s19, 1
	s_cselect_b32 s32, 1, 0
	s_mul_i32 s25, s19, s18
	s_mul_hi_u32 s27, s19, s4
	s_add_i32 s27, s27, s25
	s_mul_i32 s25, s19, s4
	s_add_u32 s38, s25, s5
	s_addc_u32 s39, s27, s11
	v_mov_b64_e32 v[4:5], 0x700
	v_cmp_lt_i64_e64 s[36:37], s[38:39], v[4:5]
	v_mov_b64_e32 v[4:5], 0x6ff
	v_cmp_gt_i64_e32 vcc, s[38:39], v[4:5]
	s_cbranch_vccnz .LBB0_341
	s_ashr_i32 s24, s38, 31
	s_lshr_b32 s24, s24, 29
	s_add_i32 s24, s38, s24
	s_ashr_i32 s25, s24, 3
	s_and_b32 s24, s24, -8
	s_sub_i32 s24, s38, s24
	s_cmp_lt_i32 s24, 0
	s_movk_i32 s26, 0xe1
	s_cselect_b32 s26, s26, 0xe0
	s_mul_i32 s24, s24, s26
	s_add_i32 s24, s24, s25
	s_mul_hi_i32 s25, s24, 0x92492493
	s_add_i32 s25, s25, s24
	s_lshr_b32 s26, s25, 31
	s_ashr_i32 s25, s25, 7
	s_add_i32 s25, s25, s26
	s_lshl_b32 s26, s25, 3
	s_sub_i32 s27, 64, s26
	s_min_i32 s27, s27, 8
	s_abs_i32 s28, s27
	v_cvt_f32_u32_e32 v4, s28
	s_sub_i32 s31, 0, s28
	s_mulk_i32 s25, 0xe0
	s_sub_i32 s25, s24, s25
	v_rcp_iflag_f32_e32 v4, v4
	s_abs_i32 s24, s25
	s_xor_b32 s29, s25, s27
	s_ashr_i32 s29, s29, 31
	v_mul_f32_e32 v4, 0x4f7ffffe, v4
	v_cvt_u32_f32_e32 v4, v4
	s_nop 0
	v_readfirstlane_b32 s33, v4
	s_mul_i32 s31, s31, s33
	s_mul_hi_u32 s31, s33, s31
	s_add_i32 s33, s33, s31
	s_mul_hi_u32 s31, s24, s33
	s_mul_i32 s33, s31, s28
	s_sub_i32 s24, s24, s33
	s_add_i32 s34, s31, 1
	s_sub_i32 s33, s24, s28
	s_cmp_ge_u32 s24, s28
	s_cselect_b32 s31, s34, s31
	s_cselect_b32 s24, s33, s24
	s_add_i32 s33, s31, 1
	s_cmp_ge_u32 s24, s28
	s_cselect_b32 s24, s33, s31
	s_xor_b32 s24, s24, s29
	s_sub_i32 s24, s24, s29
	s_mul_i32 s27, s24, s27
	s_sub_i32 s25, s25, s27
	s_add_i32 s26, s26, s25

.LBB0_342:
	s_add_u32 s33, s44, 0xfff80080
	s_addc_u32 s43, s45, -1
	s_add_i32 s50, 0, 0x10000
	s_cmp_eq_u32 s35, 28
	s_cselect_b32 s49, s27, s43
	s_cselect_b32 s48, s28, s33
	v_add_u32_e32 v142, s50, v149
	s_cselect_b32 s47, s25, s34
	s_cselect_b32 s46, s29, s31
	s_add_i32 s33, 0, 0x14000
	ds_read_b128 v[154:157], v142
	ds_read_b128 v[168:171], v142 offset:1024
	ds_read_b128 v[172:175], v142 offset:2048
	ds_read_b128 v[176:179], v142 offset:3072
	v_add_u32_e32 v142, s33, v149
	ds_read_b128 v[180:183], v142
	ds_read_b128 v[184:187], v142 offset:1024
	ds_read_b128 v[188:191], v142 offset:2048
	ds_read_b128 v[192:195], v142 offset:3072
	v_lshl_add_u64 v[142:143], s[44:45], 0, v[140:141]
	s_add_i32 m0, s12, 0xc000
	ds_read_b128 v[196:199], v167
	ds_read_b128 v[200:203], v167 offset:1024
	ds_read_b128 v[204:207], v167 offset:2048
	ds_read_b128 v[208:211], v167 offset:3072
	ds_read_b128 v[212:215], v167 offset:4096
	ds_read_b128 v[216:219], v167 offset:5120
	ds_read_b128 v[220:223], v167 offset:6144
	ds_read_b128 v[224:227], v167 offset:7168
	global_load_lds_dwordx4 v[142:143], off
	v_lshl_add_u64 v[142:143], s[44:45], 0, v[138:139]
	s_add_i32 m0, s12, 0xe000
	s_nop 0
	global_load_lds_dwordx4 v[142:143], off
	s_cmp_lg_u32 s32, 0
	s_cbranch_scc1 .Lpj_skip1
	s_waitcnt vmcnt(8)
.Lpj_skip1:
	s_waitcnt lgkmcnt(0)
	s_barrier
	s_setprio 1
	s_waitcnt lgkmcnt(0)
	v_mfma_f32_16x16x32_bf16 v[128:131], v[154:157], v[196:199], v[128:131]
	v_mfma_f32_16x16x32_bf16 v[124:127], v[172:175], v[196:199], v[124:127]
	v_mfma_f32_16x16x32_bf16 v[116:119], v[154:157], v[204:207], v[116:119]
	v_mfma_f32_16x16x32_bf16 v[108:111], v[172:175], v[204:207], v[108:111]
	v_mfma_f32_16x16x32_bf16 v[100:103], v[154:157], v[212:215], v[100:103]
	v_mfma_f32_16x16x32_bf16 v[92:95], v[172:175], v[212:215], v[92:95]
	v_mfma_f32_16x16x32_bf16 v[84:87], v[154:157], v[220:223], v[84:87]
	v_mfma_f32_16x16x32_bf16 v[76:79], v[172:175], v[220:223], v[76:79]
	v_mfma_f32_16x16x32_bf16 v[128:131], v[168:171], v[200:203], v[128:131]
	v_mfma_f32_16x16x32_bf16 v[124:127], v[176:179], v[200:203], v[124:127]
	v_mfma_f32_16x16x32_bf16 v[116:119], v[168:171], v[208:211], v[116:119]
	v_mfma_f32_16x16x32_bf16 v[108:111], v[176:179], v[208:211], v[108:111]
	v_mfma_f32_16x16x32_bf16 v[100:103], v[168:171], v[216:219], v[100:103]
	v_mfma_f32_16x16x32_bf16 v[92:95], v[176:179], v[216:219], v[92:95]
	v_mfma_f32_16x16x32_bf16 v[84:87], v[168:171], v[224:227], v[84:87]
	v_mfma_f32_16x16x32_bf16 v[76:79], v[176:179], v[224:227], v[76:79]
	s_setprio 0
	s_setprio 1
	v_mfma_f32_16x16x32_bf16 v[120:123], v[180:183], v[196:199], v[120:123]
	v_mfma_f32_16x16x32_bf16 v[112:115], v[188:191], v[196:199], v[112:115]
	v_mfma_f32_16x16x32_bf16 v[104:107], v[180:183], v[204:207], v[104:107]
	v_mfma_f32_16x16x32_bf16 v[96:99], v[188:191], v[204:207], v[96:99]
	v_mfma_f32_16x16x32_bf16 v[88:91], v[180:183], v[212:215], v[88:91]
	v_mfma_f32_16x16x32_bf16 v[80:83], v[188:191], v[212:215], v[80:83]
	v_mfma_f32_16x16x32_bf16 v[72:75], v[180:183], v[220:223], v[72:75]
	v_mfma_f32_16x16x32_bf16 v[68:71], v[188:191], v[220:223], v[68:71]
	v_mfma_f32_16x16x32_bf16 v[120:123], v[184:187], v[200:203], v[120:123]
	v_mfma_f32_16x16x32_bf16 v[112:115], v[192:195], v[200:203], v[112:115]
	v_mfma_f32_16x16x32_bf16 v[104:107], v[184:187], v[208:211], v[104:107]
	v_mfma_f32_16x16x32_bf16 v[96:99], v[192:195], v[208:211], v[96:99]
	v_mfma_f32_16x16x32_bf16 v[88:91], v[184:187], v[216:219], v[88:91]
	v_mfma_f32_16x16x32_bf16 v[80:83], v[192:195], v[216:219], v[80:83]
	v_mfma_f32_16x16x32_bf16 v[72:75], v[184:187], v[224:227], v[72:75]
	v_mfma_f32_16x16x32_bf16 v[68:71], v[192:195], v[224:227], v[68:71]
	s_setprio 0
	s_barrier
	s_add_i32 s43, s50, s10
	v_lshl_add_u64 v[142:143], s[46:47], 0, v[2:3]
	s_mov_b32 m0, s43
	ds_read_b128 v[196:199], v167 offset:16384
	ds_read_b128 v[200:203], v167 offset:17408
	ds_read_b128 v[204:207], v167 offset:18432
	ds_read_b128 v[208:211], v167 offset:19456
	ds_read_b128 v[212:215], v167 offset:20480
	ds_read_b128 v[216:219], v167 offset:21504
	ds_read_b128 v[220:223], v167 offset:22528
	ds_read_b128 v[224:227], v167 offset:23552
	global_load_lds_dwordx4 v[142:143], off
	s_add_i32 m0, s43, 0x2000
	s_add_u32 s50, s46, 0x80000
	v_lshl_add_u64 v[146:147], s[46:47], 0, v[0:1]
	s_addc_u32 s51, s47, 0
	s_add_i32 s33, s33, s10
	global_load_lds_dwordx4 v[146:147], off
	v_lshl_add_u64 v[150:151], s[50:51], 0, v[2:3]
	s_mov_b32 m0, s33
	v_lshl_add_u64 v[160:161], s[48:49], 0, v[132:133]
	global_load_lds_dwordx4 v[150:151], off
	v_lshl_add_u64 v[150:151], s[50:51], 0, v[0:1]
	s_add_i32 m0, s33, 0x2000
	s_nop 0
	global_load_lds_dwordx4 v[150:151], off
	v_lshl_add_u64 v[150:151], s[48:49], 0, v[134:135]
	s_mov_b32 m0, s12
	s_nop 0
	global_load_lds_dwordx4 v[150:151], off
	s_mov_b32 m0, s13
	s_nop 0
	global_load_lds_dwordx4 v[160:161], off
	s_cmp_lg_u32 s32, 0
	s_cbranch_scc1 .Lpj_skip2
	s_waitcnt vmcnt(8)
.Lpj_skip2:
	s_mov_b32 s32, 0
	s_waitcnt lgkmcnt(0)
	s_barrier
	s_setprio 1
	s_waitcnt lgkmcnt(0)
	v_mfma_f32_16x16x32_bf16 v[64:67], v[154:157], v[196:199], v[64:67]
	v_mfma_f32_16x16x32_bf16 v[60:63], v[172:175], v[196:199], v[60:63]
	v_mfma_f32_16x16x32_bf16 v[52:55], v[154:157], v[204:207], v[52:55]
	v_mfma_f32_16x16x32_bf16 v[44:47], v[172:175], v[204:207], v[44:47]
	v_mfma_f32_16x16x32_bf16 v[36:39], v[154:157], v[212:215], v[36:39]
	v_mfma_f32_16x16x32_bf16 v[28:31], v[172:175], v[212:215], v[28:31]
	v_mfma_f32_16x16x32_bf16 v[20:23], v[154:157], v[220:223], v[20:23]
	v_mfma_f32_16x16x32_bf16 v[12:15], v[172:175], v[220:223], v[12:15]
	v_mfma_f32_16x16x32_bf16 v[64:67], v[168:171], v[200:203], v[64:67]
	v_mfma_f32_16x16x32_bf16 v[60:63], v[176:179], v[200:203], v[60:63]
	v_mfma_f32_16x16x32_bf16 v[52:55], v[168:171], v[208:211], v[52:55]
	v_mfma_f32_16x16x32_bf16 v[44:47], v[176:179], v[208:211], v[44:47]
	v_mfma_f32_16x16x32_bf16 v[36:39], v[168:171], v[216:219], v[36:39]
	v_mfma_f32_16x16x32_bf16 v[28:31], v[176:179], v[216:219], v[28:31]
	v_mfma_f32_16x16x32_bf16 v[20:23], v[168:171], v[224:227], v[20:23]
	v_mfma_f32_16x16x32_bf16 v[12:15], v[176:179], v[224:227], v[12:15]
	s_setprio 0
	s_setprio 1
	v_mfma_f32_16x16x32_bf16 v[56:59], v[180:183], v[196:199], v[56:59]
	v_mfma_f32_16x16x32_bf16 v[48:51], v[188:191], v[196:199], v[48:51]
	v_mfma_f32_16x16x32_bf16 v[40:43], v[180:183], v[204:207], v[40:43]
	v_mfma_f32_16x16x32_bf16 v[32:35], v[188:191], v[204:207], v[32:35]
	v_mfma_f32_16x16x32_bf16 v[24:27], v[180:183], v[212:215], v[24:27]
	v_mfma_f32_16x16x32_bf16 v[16:19], v[188:191], v[212:215], v[16:19]
	v_mfma_f32_16x16x32_bf16 v[8:11], v[180:183], v[220:223], v[8:11]
	v_mfma_f32_16x16x32_bf16 v[4:7], v[188:191], v[220:223], v[4:7]
	v_mfma_f32_16x16x32_bf16 v[56:59], v[184:187], v[200:203], v[56:59]
	v_mfma_f32_16x16x32_bf16 v[48:51], v[192:195], v[200:203], v[48:51]
	v_mfma_f32_16x16x32_bf16 v[40:43], v[184:187], v[208:211], v[40:43]
	v_mfma_f32_16x16x32_bf16 v[32:35], v[192:195], v[208:211], v[32:35]
	v_mfma_f32_16x16x32_bf16 v[24:27], v[184:187], v[216:219], v[24:27]
	v_mfma_f32_16x16x32_bf16 v[16:19], v[192:195], v[216:219], v[16:19]
	v_mfma_f32_16x16x32_bf16 v[8:11], v[184:187], v[224:227], v[8:11]
	v_mfma_f32_16x16x32_bf16 v[4:7], v[192:195], v[224:227], v[4:7]
	s_setprio 0
	s_barrier
	s_add_i32 s33, 0, 0x18000
	v_add_u32_e32 v144, s33, v149
	s_add_i32 s43, 0, 0x1c000
	ds_read_b128 v[154:157], v144
	ds_read_b128 v[168:171], v144 offset:1024
	ds_read_b128 v[172:175], v144 offset:2048
	ds_read_b128 v[176:179], v144 offset:3072
	v_add_u32_e32 v144, s43, v149
	ds_read_b128 v[180:183], v144
	ds_read_b128 v[184:187], v144 offset:1024
	ds_read_b128 v[188:191], v144 offset:2048
	ds_read_b128 v[192:195], v144 offset:3072
	s_add_u32 s48, s48, 0x80000
	s_addc_u32 s49, s49, 0
	s_mov_b32 m0, s14
	v_lshl_add_u64 v[164:165], s[48:49], 0, v[134:135]
	ds_read_b128 v[196:199], v167 offset:32768
	ds_read_b128 v[200:203], v167 offset:33792
	ds_read_b128 v[204:207], v167 offset:34816
	ds_read_b128 v[208:211], v167 offset:35840
	ds_read_b128 v[212:215], v167 offset:36864
	ds_read_b128 v[216:219], v167 offset:37888
	ds_read_b128 v[220:223], v167 offset:38912
	ds_read_b128 v[224:227], v167 offset:39936
	global_load_lds_dwordx4 v[164:165], off
	v_lshl_add_u64 v[164:165], s[48:49], 0, v[132:133]
	s_mov_b32 m0, s15
	s_nop 0
	global_load_lds_dwordx4 v[164:165], off
	s_waitcnt vmcnt(8)
	s_waitcnt lgkmcnt(0)
	s_barrier
	s_setprio 1
	s_waitcnt lgkmcnt(0)
	v_mfma_f32_16x16x32_bf16 v[128:131], v[154:157], v[196:199], v[128:131]
	v_mfma_f32_16x16x32_bf16 v[124:127], v[172:175], v[196:199], v[124:127]
	v_mfma_f32_16x16x32_bf16 v[116:119], v[154:157], v[204:207], v[116:119]
	v_mfma_f32_16x16x32_bf16 v[108:111], v[172:175], v[204:207], v[108:111]
	v_mfma_f32_16x16x32_bf16 v[100:103], v[154:157], v[212:215], v[100:103]
	v_mfma_f32_16x16x32_bf16 v[92:95], v[172:175], v[212:215], v[92:95]
	v_mfma_f32_16x16x32_bf16 v[84:87], v[154:157], v[220:223], v[84:87]
	v_mfma_f32_16x16x32_bf16 v[76:79], v[172:175], v[220:223], v[76:79]
	v_mfma_f32_16x16x32_bf16 v[128:131], v[168:171], v[200:203], v[128:131]
	v_mfma_f32_16x16x32_bf16 v[124:127], v[176:179], v[200:203], v[124:127]
	v_mfma_f32_16x16x32_bf16 v[116:119], v[168:171], v[208:211], v[116:119]
	v_mfma_f32_16x16x32_bf16 v[108:111], v[176:179], v[208:211], v[108:111]
	v_mfma_f32_16x16x32_bf16 v[100:103], v[168:171], v[216:219], v[100:103]
	v_mfma_f32_16x16x32_bf16 v[92:95], v[176:179], v[216:219], v[92:95]
	v_mfma_f32_16x16x32_bf16 v[84:87], v[168:171], v[224:227], v[84:87]
	v_mfma_f32_16x16x32_bf16 v[76:79], v[176:179], v[224:227], v[76:79]
	s_setprio 0
	s_setprio 1
	v_mfma_f32_16x16x32_bf16 v[120:123], v[180:183], v[196:199], v[120:123]
	v_mfma_f32_16x16x32_bf16 v[112:115], v[188:191], v[196:199], v[112:115]
	v_mfma_f32_16x16x32_bf16 v[104:107], v[180:183], v[204:207], v[104:107]
	v_mfma_f32_16x16x32_bf16 v[96:99], v[188:191], v[204:207], v[96:99]
	v_mfma_f32_16x16x32_bf16 v[88:91], v[180:183], v[212:215], v[88:91]
	v_mfma_f32_16x16x32_bf16 v[80:83], v[188:191], v[212:215], v[80:83]
	v_mfma_f32_16x16x32_bf16 v[72:75], v[180:183], v[220:223], v[72:75]
	v_mfma_f32_16x16x32_bf16 v[68:71], v[188:191], v[220:223], v[68:71]
	v_mfma_f32_16x16x32_bf16 v[120:123], v[184:187], v[200:203], v[120:123]
	v_mfma_f32_16x16x32_bf16 v[112:115], v[192:195], v[200:203], v[112:115]
	v_mfma_f32_16x16x32_bf16 v[104:107], v[184:187], v[208:211], v[104:107]
	v_mfma_f32_16x16x32_bf16 v[96:99], v[192:195], v[208:211], v[96:99]
	v_mfma_f32_16x16x32_bf16 v[88:91], v[184:187], v[216:219], v[88:91]
	v_mfma_f32_16x16x32_bf16 v[80:83], v[192:195], v[216:219], v[80:83]
	v_mfma_f32_16x16x32_bf16 v[72:75], v[184:187], v[224:227], v[72:75]
	v_mfma_f32_16x16x32_bf16 v[68:71], v[192:195], v[224:227], v[68:71]
	s_setprio 0
	s_barrier
	s_add_i32 s33, s33, s10
	v_lshl_add_u64 v[142:143], v[142:143], 0, s[68:69]
	s_mov_b32 m0, s33
	ds_read_b128 v[196:199], v167 offset:49152
	ds_read_b128 v[200:203], v167 offset:50176
	ds_read_b128 v[204:207], v167 offset:51200
	ds_read_b128 v[208:211], v167 offset:52224
	ds_read_b128 v[212:215], v167 offset:53248
	ds_read_b128 v[216:219], v167 offset:54272
	ds_read_b128 v[220:223], v167 offset:55296
	ds_read_b128 v[224:227], v167 offset:56320
	global_load_lds_dwordx4 v[142:143], off
	s_add_i32 m0, s33, 0x2000
	s_add_u32 s46, s46, 0x80080
	v_lshl_add_u64 v[142:143], v[146:147], 0, s[68:69]
	s_addc_u32 s47, s47, 0
	s_add_i32 s33, s43, s10
	global_load_lds_dwordx4 v[142:143], off
	v_lshl_add_u64 v[142:143], s[46:47], 0, v[2:3]
	s_mov_b32 m0, s33
	s_nop 0
	global_load_lds_dwordx4 v[142:143], off
	v_lshl_add_u64 v[142:143], s[46:47], 0, v[0:1]
	s_add_i32 m0, s33, 0x2000
	s_nop 0
	global_load_lds_dwordx4 v[142:143], off
	v_lshl_add_u64 v[142:143], v[150:151], 0, s[68:69]
	s_mov_b32 m0, s16
	s_nop 0
	global_load_lds_dwordx4 v[142:143], off
	v_lshl_add_u64 v[142:143], v[160:161], 0, s[68:69]
	s_mov_b32 m0, s17
	s_nop 0
	global_load_lds_dwordx4 v[142:143], off
	s_waitcnt vmcnt(8)
	s_waitcnt lgkmcnt(0)
	s_barrier
	s_setprio 1
	s_waitcnt lgkmcnt(0)
	v_mfma_f32_16x16x32_bf16 v[64:67], v[154:157], v[196:199], v[64:67]
	v_mfma_f32_16x16x32_bf16 v[60:63], v[172:175], v[196:199], v[60:63]
	v_mfma_f32_16x16x32_bf16 v[52:55], v[154:157], v[204:207], v[52:55]
	v_mfma_f32_16x16x32_bf16 v[44:47], v[172:175], v[204:207], v[44:47]
	v_mfma_f32_16x16x32_bf16 v[36:39], v[154:157], v[212:215], v[36:39]
	v_mfma_f32_16x16x32_bf16 v[28:31], v[172:175], v[212:215], v[28:31]
	v_mfma_f32_16x16x32_bf16 v[20:23], v[154:157], v[220:223], v[20:23]
	v_mfma_f32_16x16x32_bf16 v[12:15], v[172:175], v[220:223], v[12:15]
	v_mfma_f32_16x16x32_bf16 v[64:67], v[168:171], v[200:203], v[64:67]
	v_mfma_f32_16x16x32_bf16 v[60:63], v[176:179], v[200:203], v[60:63]
	v_mfma_f32_16x16x32_bf16 v[52:55], v[168:171], v[208:211], v[52:55]
	v_mfma_f32_16x16x32_bf16 v[44:47], v[176:179], v[208:211], v[44:47]
	v_mfma_f32_16x16x32_bf16 v[36:39], v[168:171], v[216:219], v[36:39]
	v_mfma_f32_16x16x32_bf16 v[28:31], v[176:179], v[216:219], v[28:31]
	v_mfma_f32_16x16x32_bf16 v[20:23], v[168:171], v[224:227], v[20:23]
	v_mfma_f32_16x16x32_bf16 v[12:15], v[176:179], v[224:227], v[12:15]
	s_setprio 0
	s_setprio 1
	v_mfma_f32_16x16x32_bf16 v[56:59], v[180:183], v[196:199], v[56:59]
	v_mfma_f32_16x16x32_bf16 v[48:51], v[188:191], v[196:199], v[48:51]
	v_mfma_f32_16x16x32_bf16 v[40:43], v[180:183], v[204:207], v[40:43]
	v_mfma_f32_16x16x32_bf16 v[32:35], v[188:191], v[204:207], v[32:35]
	v_mfma_f32_16x16x32_bf16 v[24:27], v[180:183], v[212:215], v[24:27]
	v_mfma_f32_16x16x32_bf16 v[16:19], v[188:191], v[212:215], v[16:19]
	v_mfma_f32_16x16x32_bf16 v[8:11], v[180:183], v[220:223], v[8:11]
	v_mfma_f32_16x16x32_bf16 v[4:7], v[188:191], v[220:223], v[4:7]
	v_mfma_f32_16x16x32_bf16 v[56:59], v[184:187], v[200:203], v[56:59]
	v_mfma_f32_16x16x32_bf16 v[48:51], v[192:195], v[200:203], v[48:51]
	v_mfma_f32_16x16x32_bf16 v[40:43], v[184:187], v[208:211], v[40:43]
	v_mfma_f32_16x16x32_bf16 v[32:35], v[192:195], v[208:211], v[32:35]
	v_mfma_f32_16x16x32_bf16 v[24:27], v[184:187], v[216:219], v[24:27]
	v_mfma_f32_16x16x32_bf16 v[16:19], v[192:195], v[216:219], v[16:19]
	v_mfma_f32_16x16x32_bf16 v[8:11], v[184:187], v[224:227], v[8:11]
	v_mfma_f32_16x16x32_bf16 v[4:7], v[192:195], v[224:227], v[4:7]
	s_setprio 0
	s_barrier
	s_add_i32 s35, s35, 2
	s_add_u32 s31, s31, 0x100
	s_addc_u32 s34, s34, 0
	s_add_u32 s44, s44, 0x100
	s_addc_u32 s45, s45, 0
	s_cmp_gt_u32 s35, 29
	s_cbranch_scc0 .LBB0_342
	s_and_b64 vcc, exec, s[22:23]
	s_cbranch_vccz .LBB0_345
	s_barrier
.LBB0_345:
	v_lshl_add_u32 v168, s42, 8, v145
	v_or_b32_e32 v164, 16, v168
	v_or_b32_e32 v160, 32, v168
	v_or_b32_e32 v156, 48, v168
	v_add_u32_e32 v154, 0x80, v168
	v_add_u32_e32 v150, 0x90, v168
	v_add_u32_e32 v146, 0xa0, v168
	v_add_u32_e32 v142, 0xb0, v168
	s_cmp_eq_u32 s42, s98
	s_cbranch_scc1 .Lpj_scales_ready
	s_mov_b32 s98, s42
	v_mad_u64_u32 v[188:189], s[28:29], v168, 32, v[136:137]
	v_mad_u64_u32 v[190:191], s[28:29], v164, 32, v[136:137]
	v_mad_u64_u32 v[192:193], s[28:29], v160, 32, v[136:137]
	v_mad_u64_u32 v[194:195], s[28:29], v156, 32, v[136:137]
	v_mad_u64_u32 v[196:197], s[28:29], v154, 32, v[136:137]
	v_mad_u64_u32 v[198:199], s[28:29], v150, 32, v[136:137]
	v_mad_u64_u32 v[200:201], s[28:29], v146, 32, v[136:137]
	v_mad_u64_u32 v[202:203], s[28:29], v142, 32, v[136:137]
	global_load_dwordx2 v[170:171], v[188:189], off
	global_load_dwordx2 v[172:173], v[190:191], off
	global_load_dwordx2 v[174:175], v[192:193], off
	global_load_dwordx2 v[176:177], v[194:195], off
	global_load_dwordx2 v[178:179], v[196:197], off
	global_load_dwordx2 v[180:181], v[198:199], off
	global_load_dwordx2 v[182:183], v[200:201], off
	global_load_dwordx2 v[184:185], v[202:203], off
	s_waitcnt vmcnt(0)
	v_add_f32_e32 v170, v170, v171
	v_add_f32_e32 v172, v172, v173
	v_add_f32_e32 v174, v174, v175
	v_add_f32_e32 v176, v176, v177
	v_add_f32_e32 v178, v178, v179
	v_add_f32_e32 v180, v180, v181
	v_add_f32_e32 v182, v182, v183
	v_add_f32_e32 v184, v184, v185
	ds_bpermute_b32 v171, v153, v170
	ds_bpermute_b32 v173, v153, v172
	ds_bpermute_b32 v175, v153, v174
	ds_bpermute_b32 v177, v153, v176
	ds_bpermute_b32 v179, v153, v178
	ds_bpermute_b32 v181, v153, v180
	ds_bpermute_b32 v183, v153, v182
	ds_bpermute_b32 v185, v153, v184
	s_waitcnt lgkmcnt(0)
	v_add_f32_e32 v170, v170, v171
	v_add_f32_e32 v172, v172, v173
	v_add_f32_e32 v174, v174, v175
	v_add_f32_e32 v176, v176, v177
	v_add_f32_e32 v178, v178, v179
	v_add_f32_e32 v180, v180, v181
	v_add_f32_e32 v182, v182, v183
	v_add_f32_e32 v184, v184, v185
	ds_bpermute_b32 v171, v159, v170
	ds_bpermute_b32 v173, v159, v172
	ds_bpermute_b32 v175, v159, v174
	ds_bpermute_b32 v177, v159, v176
	ds_bpermute_b32 v179, v159, v178
	ds_bpermute_b32 v181, v159, v180
	ds_bpermute_b32 v183, v159, v182
	ds_bpermute_b32 v185, v159, v184
	s_waitcnt lgkmcnt(0)
	v_add_f32_e32 v170, v170, v171
	v_add_f32_e32 v172, v172, v173
	v_add_f32_e32 v174, v174, v175
	v_add_f32_e32 v176, v176, v177
	v_add_f32_e32 v178, v178, v179
	v_add_f32_e32 v180, v180, v181
	v_add_f32_e32 v182, v182, v183
	v_add_f32_e32 v184, v184, v185
	v_fmamk_f32 v170, v170, 0x3a000000, v232
	v_fmamk_f32 v172, v172, 0x3a000000, v232
	v_fmamk_f32 v174, v174, 0x3a000000, v232
	v_fmamk_f32 v176, v176, 0x3a000000, v232
	v_fmamk_f32 v178, v178, 0x3a000000, v232
	v_fmamk_f32 v180, v180, 0x3a000000, v232
	v_fmamk_f32 v182, v182, 0x3a000000, v232
	v_fmamk_f32 v184, v184, 0x3a000000, v232
	v_rsq_f32_e32 v228, v170
	v_rsq_f32_e32 v230, v172
	v_rsq_f32_e32 v238, v174
	v_rsq_f32_e32 v242, v176
	v_rsq_f32_e32 v244, v178
	v_rsq_f32_e32 v246, v180
	v_rsq_f32_e32 v248, v182
	v_rsq_f32_e32 v250, v184
	s_nop 0
.Lpj_scales_ready:
	s_movk_i32 s33, 0x3800
	v_mov_b64_e32 v[170:171], s[20:21]
	v_lshl_or_b32 v176, s30, 8, v163
	v_ashrrev_i32_e32 v177, 31, v176
	v_lshlrev_b64 v[176:177], 1, v[176:177]
	v_mad_i64_i32 v[204:205], s[28:29], v168, s33, v[170:171]
	v_mad_i64_i32 v[206:207], s[28:29], v164, s33, v[170:171]
	v_mad_i64_i32 v[208:209], s[28:29], v160, s33, v[170:171]
	v_mad_i64_i32 v[210:211], s[28:29], v156, s33, v[170:171]
	v_mad_i64_i32 v[212:213], s[28:29], v154, s33, v[170:171]
	v_mad_i64_i32 v[214:215], s[28:29], v150, s33, v[170:171]
	v_mad_i64_i32 v[216:217], s[28:29], v146, s33, v[170:171]
	v_mad_i64_i32 v[218:219], s[28:29], v142, s33, v[170:171]
	v_lshl_add_u64 v[204:205], v[204:205], 0, v[176:177]
	v_lshl_add_u64 v[206:207], v[206:207], 0, v[176:177]
	v_lshl_add_u64 v[208:209], v[208:209], 0, v[176:177]
	v_lshl_add_u64 v[210:211], v[210:211], 0, v[176:177]
	v_lshl_add_u64 v[212:213], v[212:213], 0, v[176:177]
	v_lshl_add_u64 v[214:215], v[214:215], 0, v[176:177]
	v_lshl_add_u64 v[216:217], v[216:217], 0, v[176:177]
	v_lshl_add_u64 v[218:219], v[218:219], 0, v[176:177]
	s_mov_b64 s[42:43], -1
	s_andn2_b64 vcc, exec, s[36:37]
	v_pk_mul_f32 v[128:129], v[128:129], v[228:229] op_sel_hi:[1,0]
	v_pk_mul_f32 v[130:131], v[130:131], v[228:229] op_sel_hi:[1,0]
	v_pk_mul_f32 v[124:125], v[124:125], v[228:229] op_sel_hi:[1,0]
	v_pk_mul_f32 v[126:127], v[126:127], v[228:229] op_sel_hi:[1,0]
	v_cvt_pk_bf16_f32 v128, v128, v129
	v_cvt_pk_bf16_f32 v129, v130, v131
	v_cvt_pk_bf16_f32 v130, v124, v125
	v_cvt_pk_bf16_f32 v131, v126, v127
	s_waitcnt vmcnt(0)
	global_store_dwordx4 v[204:205], v[128:131], off
	v_pk_mul_f32 v[120:121], v[120:121], v[228:229] op_sel_hi:[1,0]
	v_pk_mul_f32 v[122:123], v[122:123], v[228:229] op_sel_hi:[1,0]
	v_pk_mul_f32 v[112:113], v[112:113], v[228:229] op_sel_hi:[1,0]
	v_pk_mul_f32 v[114:115], v[114:115], v[228:229] op_sel_hi:[1,0]
	v_cvt_pk_bf16_f32 v120, v120, v121
	v_cvt_pk_bf16_f32 v121, v122, v123
	v_cvt_pk_bf16_f32 v122, v112, v113
	v_cvt_pk_bf16_f32 v123, v114, v115
	global_store_dwordx4 v[204:205], v[120:123], off offset:256
	v_pk_mul_f32 v[116:117], v[116:117], v[230:231] op_sel_hi:[1,0]
	v_pk_mul_f32 v[118:119], v[118:119], v[230:231] op_sel_hi:[1,0]
	v_pk_mul_f32 v[108:109], v[108:109], v[230:231] op_sel_hi:[1,0]
	v_pk_mul_f32 v[110:111], v[110:111], v[230:231] op_sel_hi:[1,0]
	v_cvt_pk_bf16_f32 v116, v116, v117
	v_cvt_pk_bf16_f32 v117, v118, v119
	v_cvt_pk_bf16_f32 v118, v108, v109
	v_cvt_pk_bf16_f32 v119, v110, v111
	global_store_dwordx4 v[206:207], v[116:119], off
	v_pk_mul_f32 v[104:105], v[104:105], v[230:231] op_sel_hi:[1,0]
	v_pk_mul_f32 v[106:107], v[106:107], v[230:231] op_sel_hi:[1,0]
	v_pk_mul_f32 v[96:97], v[96:97], v[230:231] op_sel_hi:[1,0]
	v_pk_mul_f32 v[98:99], v[98:99], v[230:231] op_sel_hi:[1,0]
	v_cvt_pk_bf16_f32 v104, v104, v105
	v_cvt_pk_bf16_f32 v105, v106, v107
	v_cvt_pk_bf16_f32 v106, v96, v97
	v_cvt_pk_bf16_f32 v107, v98, v99
	global_store_dwordx4 v[206:207], v[104:107], off offset:256
	v_pk_mul_f32 v[100:101], v[100:101], v[238:239] op_sel_hi:[1,0]
	v_pk_mul_f32 v[102:103], v[102:103], v[238:239] op_sel_hi:[1,0]
	v_pk_mul_f32 v[92:93], v[92:93], v[238:239] op_sel_hi:[1,0]
	v_pk_mul_f32 v[94:95], v[94:95], v[238:239] op_sel_hi:[1,0]
	v_cvt_pk_bf16_f32 v100, v100, v101
	v_cvt_pk_bf16_f32 v101, v102, v103
	v_cvt_pk_bf16_f32 v102, v92, v93
	v_cvt_pk_bf16_f32 v103, v94, v95
	global_store_dwordx4 v[208:209], v[100:103], off
	v_pk_mul_f32 v[88:89], v[88:89], v[238:239] op_sel_hi:[1,0]
	v_pk_mul_f32 v[90:91], v[90:91], v[238:239] op_sel_hi:[1,0]
	v_pk_mul_f32 v[80:81], v[80:81], v[238:239] op_sel_hi:[1,0]
	v_pk_mul_f32 v[82:83], v[82:83], v[238:239] op_sel_hi:[1,0]
	v_cvt_pk_bf16_f32 v88, v88, v89
	v_cvt_pk_bf16_f32 v89, v90, v91
	v_cvt_pk_bf16_f32 v90, v80, v81
	v_cvt_pk_bf16_f32 v91, v82, v83
	global_store_dwordx4 v[208:209], v[88:91], off offset:256
	v_pk_mul_f32 v[84:85], v[84:85], v[242:243] op_sel_hi:[1,0]
	v_pk_mul_f32 v[86:87], v[86:87], v[242:243] op_sel_hi:[1,0]
	v_pk_mul_f32 v[76:77], v[76:77], v[242:243] op_sel_hi:[1,0]
	v_pk_mul_f32 v[78:79], v[78:79], v[242:243] op_sel_hi:[1,0]
	v_cvt_pk_bf16_f32 v84, v84, v85
	v_cvt_pk_bf16_f32 v85, v86, v87
	v_cvt_pk_bf16_f32 v86, v76, v77
	v_cvt_pk_bf16_f32 v87, v78, v79
	global_store_dwordx4 v[210:211], v[84:87], off
	v_pk_mul_f32 v[72:73], v[72:73], v[242:243] op_sel_hi:[1,0]
	v_pk_mul_f32 v[74:75], v[74:75], v[242:243] op_sel_hi:[1,0]
	v_pk_mul_f32 v[68:69], v[68:69], v[242:243] op_sel_hi:[1,0]
	v_pk_mul_f32 v[70:71], v[70:71], v[242:243] op_sel_hi:[1,0]
	v_cvt_pk_bf16_f32 v72, v72, v73
	v_cvt_pk_bf16_f32 v73, v74, v75
	v_cvt_pk_bf16_f32 v74, v68, v69
	v_cvt_pk_bf16_f32 v75, v70, v71
	global_store_dwordx4 v[210:211], v[72:75], off offset:256
	v_pk_mul_f32 v[64:65], v[64:65], v[244:245] op_sel_hi:[1,0]
	v_pk_mul_f32 v[66:67], v[66:67], v[244:245] op_sel_hi:[1,0]
	v_pk_mul_f32 v[60:61], v[60:61], v[244:245] op_sel_hi:[1,0]
	v_pk_mul_f32 v[62:63], v[62:63], v[244:245] op_sel_hi:[1,0]
	v_cvt_pk_bf16_f32 v64, v64, v65
	v_cvt_pk_bf16_f32 v65, v66, v67
	v_cvt_pk_bf16_f32 v66, v60, v61
	v_cvt_pk_bf16_f32 v67, v62, v63
	global_store_dwordx4 v[212:213], v[64:67], off
	v_pk_mul_f32 v[56:57], v[56:57], v[244:245] op_sel_hi:[1,0]
	v_pk_mul_f32 v[58:59], v[58:59], v[244:245] op_sel_hi:[1,0]
	v_pk_mul_f32 v[48:49], v[48:49], v[244:245] op_sel_hi:[1,0]
	v_pk_mul_f32 v[50:51], v[50:51], v[244:245] op_sel_hi:[1,0]
	v_cvt_pk_bf16_f32 v56, v56, v57
	v_cvt_pk_bf16_f32 v57, v58, v59
	v_cvt_pk_bf16_f32 v58, v48, v49
	v_cvt_pk_bf16_f32 v59, v50, v51
	global_store_dwordx4 v[212:213], v[56:59], off offset:256
	v_pk_mul_f32 v[52:53], v[52:53], v[246:247] op_sel_hi:[1,0]
	v_pk_mul_f32 v[54:55], v[54:55], v[246:247] op_sel_hi:[1,0]
	v_pk_mul_f32 v[44:45], v[44:45], v[246:247] op_sel_hi:[1,0]
	v_pk_mul_f32 v[46:47], v[46:47], v[246:247] op_sel_hi:[1,0]
	v_cvt_pk_bf16_f32 v52, v52, v53
	v_cvt_pk_bf16_f32 v53, v54, v55
	v_cvt_pk_bf16_f32 v54, v44, v45
	v_cvt_pk_bf16_f32 v55, v46, v47
	global_store_dwordx4 v[214:215], v[52:55], off
	v_pk_mul_f32 v[40:41], v[40:41], v[246:247] op_sel_hi:[1,0]
	v_pk_mul_f32 v[42:43], v[42:43], v[246:247] op_sel_hi:[1,0]
	v_pk_mul_f32 v[32:33], v[32:33], v[246:247] op_sel_hi:[1,0]
	v_pk_mul_f32 v[34:35], v[34:35], v[246:247] op_sel_hi:[1,0]
	v_cvt_pk_bf16_f32 v40, v40, v41
	v_cvt_pk_bf16_f32 v41, v42, v43
	v_cvt_pk_bf16_f32 v42, v32, v33
	v_cvt_pk_bf16_f32 v43, v34, v35
	global_store_dwordx4 v[214:215], v[40:43], off offset:256
	v_pk_mul_f32 v[36:37], v[36:37], v[248:249] op_sel_hi:[1,0]
	v_pk_mul_f32 v[38:39], v[38:39], v[248:249] op_sel_hi:[1,0]
	v_pk_mul_f32 v[28:29], v[28:29], v[248:249] op_sel_hi:[1,0]
	v_pk_mul_f32 v[30:31], v[30:31], v[248:249] op_sel_hi:[1,0]
	v_cvt_pk_bf16_f32 v36, v36, v37
	v_cvt_pk_bf16_f32 v37, v38, v39
	v_cvt_pk_bf16_f32 v38, v28, v29
	v_cvt_pk_bf16_f32 v39, v30, v31
	global_store_dwordx4 v[216:217], v[36:39], off
	v_pk_mul_f32 v[24:25], v[24:25], v[248:249] op_sel_hi:[1,0]
	v_pk_mul_f32 v[26:27], v[26:27], v[248:249] op_sel_hi:[1,0]
	v_pk_mul_f32 v[16:17], v[16:17], v[248:249] op_sel_hi:[1,0]
	v_pk_mul_f32 v[18:19], v[18:19], v[248:249] op_sel_hi:[1,0]
	v_cvt_pk_bf16_f32 v24, v24, v25
	v_cvt_pk_bf16_f32 v25, v26, v27
	v_cvt_pk_bf16_f32 v26, v16, v17
	v_cvt_pk_bf16_f32 v27, v18, v19
	global_store_dwordx4 v[216:217], v[24:27], off offset:256
	v_pk_mul_f32 v[20:21], v[20:21], v[250:251] op_sel_hi:[1,0]
	v_pk_mul_f32 v[22:23], v[22:23], v[250:251] op_sel_hi:[1,0]
	v_pk_mul_f32 v[12:13], v[12:13], v[250:251] op_sel_hi:[1,0]
	v_pk_mul_f32 v[14:15], v[14:15], v[250:251] op_sel_hi:[1,0]
	v_cvt_pk_bf16_f32 v20, v20, v21
	v_cvt_pk_bf16_f32 v21, v22, v23
	v_cvt_pk_bf16_f32 v22, v12, v13
	v_cvt_pk_bf16_f32 v23, v14, v15
	global_store_dwordx4 v[218:219], v[20:23], off
	v_pk_mul_f32 v[8:9], v[8:9], v[250:251] op_sel_hi:[1,0]
	v_pk_mul_f32 v[10:11], v[10:11], v[250:251] op_sel_hi:[1,0]
	v_pk_mul_f32 v[4:5], v[4:5], v[250:251] op_sel_hi:[1,0]
	v_pk_mul_f32 v[6:7], v[6:7], v[250:251] op_sel_hi:[1,0]
	v_cvt_pk_bf16_f32 v8, v8, v9
	v_cvt_pk_bf16_f32 v9, v10, v11
	v_cvt_pk_bf16_f32 v10, v4, v5
	v_cvt_pk_bf16_f32 v11, v6, v7
	global_store_dwordx4 v[218:219], v[8:11], off offset:256
	s_cbranch_vccnz .LBB0_338
	s_andn2_b64 vcc, exec, s[2:3]
	s_cbranch_vccnz .LBB0_337
	s_barrier
	s_branch .LBB0_337

.LBB0_366:
	v_readlane_b32 s6, v254, 17
	v_readlane_b32 s7, v254, 18
	v_cvt_f32_u32_e32 v1, v2
	v_sub_u32_e32 v5, 0, v2
	v_rcp_iflag_f32_e32 v1, v1
	s_nop 1
	global_atomic_add v4, v3, v233, s[6:7] sc0
	v_mul_f32_e32 v1, 0x4f7ffffe, v1
	v_cvt_u32_f32_e32 v1, v1
	v_mul_lo_u32 v5, v5, v1
	v_mul_hi_u32 v5, v1, v5
	v_add_u32_e32 v1, v1, v5
	s_waitcnt vmcnt(0)
	v_mul_hi_u32 v1, v4, v1
	v_mul_lo_u32 v5, v1, v2
	v_sub_u32_e32 v5, v4, v5
	v_add_u32_e32 v6, 1, v1
	v_cmp_ge_u32_e32 vcc, v5, v2
	v_add_u32_e32 v4, 1, v4
	s_nop 0
	v_cndmask_b32_e32 v1, v1, v6, vcc
	v_sub_u32_e32 v6, v5, v2
	v_cndmask_b32_e32 v5, v5, v6, vcc
	v_add_u32_e32 v6, 1, v1
	v_cmp_ge_u32_e32 vcc, v5, v2
	s_nop 1
	v_cndmask_b32_e32 v1, v1, v6, vcc
	v_mul_lo_u32 v5, v2, v1
	v_add_u32_e32 v2, v5, v2
	v_cmp_ne_u32_e32 vcc, v4, v2
	s_and_saveexec_b64 s[6:7], vcc
	s_xor_b64 s[20:21], exec, s[6:7]
	s_cbranch_execz .LBB0_380
	v_readlane_b32 s6, v254, 19
	v_readlane_b32 s7, v254, 20
	s_waitcnt lgkmcnt(0)
	s_nop 3
	buffer_inv sc1
	global_load_dword v0, v3, s[6:7] sc1
	s_waitcnt vmcnt(0)
	v_cmp_eq_u32_e32 vcc, v0, v1
	s_and_saveexec_b64 s[22:23], vcc
	s_cbranch_execz .LBB0_379
	s_mov_b32 s5, 1
	s_mov_b64 s[24:25], 0
	s_branch .LBB0_370

.LBB0_379:
	s_or_b64 exec, exec, s[22:23]
	s_waitcnt vmcnt(0)
	s_waitcnt vmcnt(0)

.LBB0_1056:
	v_readlane_b32 s0, v253, 12
	v_readlane_b32 s1, v253, 13
	s_cmp_le_i32 s0, s4
	s_cselect_b64 s[0:1], -1, 0
	s_and_b64 s[0:1], s[0:1], s[2:3]
	s_andn2_b64 vcc, exec, s[0:1]
	s_cbranch_vccnz .LBB0_1073
	s_mov_b64 s[24:25], s[76:77]
	s_load_dword s50, s[58:59], 0x0
	s_mov_b32 s51, s74
	v_mov_b32_e32 v18, v235
	s_waitcnt lgkmcnt(0)
	s_cmpk_gt_i32 s51, 0xaff
	v_readfirstlane_b32 s5, v18
	s_cbranch_scc1 .LBB0_1073
	s_mov_b32 s98, -1
	v_lshlrev_b32_e32 v1, 4, v18
	v_add_u32_e32 v0, 0x2000, v1
	v_ashrrev_i32_e32 v2, 31, v0
	v_lshrrev_b32_e32 v2, 22, v2
	v_add_u32_e32 v2, v0, v2
	v_ashrrev_i32_e32 v12, 10, v2
	v_mul_i32_i24_e32 v2, 0x400, v12
	v_sub_u32_e32 v0, v0, v2
	v_lshrrev_b32_e32 v2, 4, v0
	v_readlane_b32 s2, v254, 59
	v_bitop3_b32 v0, v2, v0, 32 bitop3:0x6c
	v_readlane_b32 s3, v254, 60
	s_mov_b32 s4, s2
	s_add_u32 s52, s24, 0x22100000
	v_ashrrev_i32_e32 v2, 31, v0
	s_mul_i32 s3, s4, 0x2c00000
	s_addc_u32 s53, s25, 0
	v_lshrrev_b32_e32 v2, 26, v2
	s_mul_hi_u32 s2, s2, 0x2c00000
	s_add_u32 s3, s24, s3
	v_add_u32_e32 v2, v0, v2
	v_lshlrev_b32_e32 v4, 3, v12
	s_addc_u32 s2, s25, s2
	v_ashrrev_i32_e32 v13, 6, v2
	v_and_b32_e32 v4, -16, v4
	s_add_u32 s54, s3, 0x11900000
	v_add_u32_e32 v4, v13, v4
	s_addc_u32 s55, s2, 0
	v_and_b32_e32 v5, 3, v13
	s_mov_b32 s2, 0xfffe0
	v_lshrrev_b32_e32 v6, 2, v4
	v_lshlrev_b32_e32 v7, 1, v4
	v_and_b32_e32 v2, 0xc0, v2
	v_and_or_b32 v5, v4, s2, v5
	v_and_b32_e32 v6, 4, v6
	v_and_b32_e32 v7, 24, v7
	v_sub_u32_e32 v0, v0, v2
	v_or3_b32 v5, v5, v6, v7
	v_lshlrev_b32_e32 v6, 5, v12
	v_ashrrev_i16_sdwa v0, v233, sext(v0) dst_sel:DWORD dst_unused:UNUSED_PAD src0_sel:DWORD src1_sel:BYTE_0
	v_and_b32_e32 v6, 32, v6
	v_bfe_i32 v14, v0, 0, 16
	v_add_lshl_u32 v2, v6, v14, 1
	v_lshl_add_u32 v0, v5, 12, v2
	v_lshl_add_u32 v132, v4, 12, v2
	v_bfe_i32 v2, v18, 27, 1
	v_lshrrev_b32_e32 v2, 22, v2
	v_add_u32_e32 v2, v1, v2
	v_and_b32_e32 v2, 0xfffffc00, v2
	v_sub_u32_e32 v1, v1, v2
	v_lshrrev_b32_e32 v2, 4, v1
	v_ashrrev_i32_e32 v4, 31, v18
	v_bitop3_b32 v1, v2, v1, 32 bitop3:0x6c
	v_lshrrev_b32_e32 v4, 26, v4
	v_ashrrev_i32_e32 v2, 31, v1
	v_add_u32_e32 v4, v18, v4
	v_lshrrev_b32_e32 v2, 26, v2
	v_ashrrev_i32_e32 v16, 6, v4
	v_add_u32_e32 v2, v1, v2
	v_lshlrev_b32_e32 v4, 3, v16
	v_ashrrev_i32_e32 v15, 6, v2
	v_and_b32_e32 v4, -16, v4
	v_add_u32_e32 v4, v15, v4
	v_and_b32_e32 v5, 3, v15
	s_ashr_i32 s57, s51, 31
	v_and_or_b32 v5, v4, s2, v5
	s_lshr_b32 s2, s57, 29
	s_add_i32 s2, s51, s2
	s_ashr_i32 s6, s5, 6
	s_ashr_i32 s3, s2, 3
	s_and_b32 s2, s2, -8
	s_ashr_i32 s7, s5, 8
	s_lshl_b32 s56, s6, 10
	s_sub_i32 s2, s51, s2
	s_cmp_lt_i32 s2, 0
	s_movk_i32 s4, 0x161
	s_cselect_b32 s4, s4, 0x160
	s_mul_i32 s2, s2, s4
	s_add_i32 s2, s2, s3
	s_mul_hi_i32 s3, s2, 0x2e8ba2e9
	s_lshr_b32 s4, s3, 31
	s_ashr_i32 s3, s3, 6
	s_add_i32 s3, s3, s4
	s_lshl_b32 s4, s3, 3
	s_mulk_i32 s3, 0x160
	s_sub_i32 s2, s2, s3
	s_bfe_u32 s3, s2, 0x3001c
	s_add_i32 s3, s2, s3
	s_sext_i32_i16 s8, s3
	s_and_b32 s3, s3, 0xfff8
	s_sub_i32 s2, s2, s3
	s_sext_i32_i16 s2, s2
	v_lshrrev_b32_e32 v6, 2, v4
	v_lshlrev_b32_e32 v7, 1, v4
	v_and_b32_e32 v2, 0xc0, v2
	s_lshr_b32 s20, s8, 3
	s_add_i32 s42, s4, s2
	v_and_b32_e32 v6, 4, v6
	v_and_b32_e32 v7, 24, v7
	v_sub_u32_e32 v1, v1, v2
	s_ashr_i32 s43, s42, 31
	s_bfe_i64 s[8:9], s[20:21], 0x100000
	v_or3_b32 v5, v5, v6, v7
	v_lshlrev_b32_e32 v6, 5, v16
	v_ashrrev_i16_sdwa v1, v233, sext(v1) dst_sel:DWORD dst_unused:UNUSED_PAD src0_sel:DWORD src1_sel:BYTE_0
	s_lshl_b64 s[2:3], s[42:43], 20
	s_lshl_b64 s[8:9], s[8:9], 20
	v_and_b32_e32 v6, 32, v6
	v_bfe_i32 v17, v1, 0, 16
	s_add_u32 s44, s54, s8
	v_add_lshl_u32 v1, v6, v17, 1
	s_addc_u32 s45, s55, s9
	s_add_i32 s60, s56, 0
	v_lshl_add_u32 v2, v5, 12, v1
	s_add_i32 m0, s60, 0x10000
	v_lshl_add_u32 v134, v4, 12, v1
	global_load_lds_dwordx4 v2, s[44:45]
	s_add_i32 m0, s60, 0x12000
	s_add_u32 s8, s44, 0x80000
	global_load_lds_dwordx4 v0, s[44:45]
	s_addc_u32 s9, s45, 0
	s_add_i32 m0, s60, 0x14000
	v_mov_b32_e32 v1, v3
	global_load_lds_dwordx4 v2, s[8:9]
	s_add_i32 m0, s60, 0x16000
	s_add_u32 s46, s52, s2
	s_addc_u32 s47, s53, s3
	s_add_i32 s61, s60, 0x2000
	global_load_lds_dwordx4 v0, s[8:9]
	s_mov_b32 m0, s60
	s_add_u32 s2, s46, 0x80000
	global_load_lds_dwordx4 v134, s[46:47]
	s_mov_b32 m0, s61
	s_addc_u32 s3, s47, 0
	s_add_i32 s62, s60, 0x4000
	global_load_lds_dwordx4 v132, s[46:47]
	s_mov_b32 m0, s62
	s_add_i32 s63, s60, 0x6000
	global_load_lds_dwordx4 v134, s[2:3]
	s_mov_b32 m0, s63
	v_mov_b32_e32 v135, v3
	global_load_lds_dwordx4 v132, s[2:3]
	v_mov_b32_e32 v133, v3
	s_cmp_eq_u32 s7, 1
	v_lshl_add_u64 v[10:11], s[44:45], 0, v[2:3]
	v_lshl_add_u64 v[8:9], s[44:45], 0, v[0:1]
	v_lshl_add_u64 v[4:5], s[46:47], 0, v[134:135]
	s_cselect_b64 s[2:3], -1, 0
	s_cmp_lg_u32 s7, 1
	v_lshl_add_u64 v[6:7], s[46:47], 0, v[132:133]
	s_cbranch_scc1 .LBB0_1060
	s_barrier

.LBB0_1063:
	s_add_i32 s71, s71, 1
	s_cmp_gt_u32 s71, 1
	s_cselect_b32 s32, 1, 0
	s_mul_i32 s5, s71, s70
	s_mul_hi_u32 s6, s71, s50
	s_add_i32 s6, s6, s5
	s_mul_i32 s5, s71, s50
	s_add_u32 s38, s5, s51
	s_addc_u32 s39, s6, s57
	v_mov_b64_e32 v[4:5], 0xb00
	v_cmp_lt_i64_e64 s[36:37], s[38:39], v[4:5]
	v_mov_b64_e32 v[4:5], 0xaff
	v_cmp_gt_i64_e32 vcc, s[38:39], v[4:5]
	s_cbranch_vccnz .LBB0_1065
	s_ashr_i32 s5, s38, 31
	s_lshr_b32 s5, s5, 29
	s_add_i32 s5, s38, s5
	s_ashr_i32 s6, s5, 3
	s_and_b32 s5, s5, -8
	s_sub_i32 s5, s38, s5
	s_cmp_lt_i32 s5, 0
	s_movk_i32 s7, 0x161
	s_cselect_b32 s7, s7, 0x160
	s_mul_i32 s5, s5, s7
	s_add_i32 s5, s5, s6
	s_mul_hi_i32 s6, s5, 0x2e8ba2e9
	s_lshr_b32 s7, s6, 31
	s_ashr_i32 s6, s6, 6
	s_add_i32 s6, s6, s7
	s_lshl_b32 s7, s6, 3
	s_sub_i32 s8, 64, s7
	s_min_i32 s8, s8, 8
	s_abs_i32 s9, s8
	v_cvt_f32_u32_e32 v4, s9
	s_sub_i32 s11, 0, s9
	s_mulk_i32 s6, 0x160
	s_sub_i32 s5, s5, s6
	v_rcp_iflag_f32_e32 v4, v4
	s_abs_i32 s6, s5
	s_xor_b32 s10, s5, s8
	s_ashr_i32 s10, s10, 31
	v_mul_f32_e32 v4, 0x4f7ffffe, v4
	v_cvt_u32_f32_e32 v4, v4
	s_nop 0
	v_readfirstlane_b32 s12, v4
	s_mul_i32 s11, s11, s12
	s_mul_hi_u32 s11, s12, s11
	s_add_i32 s12, s12, s11
	s_mul_hi_u32 s11, s6, s12
	s_mul_i32 s12, s11, s9
	s_sub_i32 s6, s6, s12
	s_add_i32 s13, s11, 1
	s_sub_i32 s12, s6, s9
	s_cmp_ge_u32 s6, s9
	s_cselect_b32 s11, s13, s11
	s_cselect_b32 s6, s12, s6
	s_add_i32 s12, s11, 1
	s_cmp_ge_u32 s6, s9
	s_cselect_b32 s6, s12, s11
	s_xor_b32 s6, s6, s10
	s_sub_i32 s24, s6, s10
	s_mul_i32 s6, s24, s8
	s_sub_i32 s5, s5, s6
	s_add_i32 s26, s7, s5

.LBB0_1066:
	s_add_u32 s12, s44, 0xfff80080
	s_addc_u32 s13, s45, -1
	s_add_i32 s14, 0, 0x10000
	s_cmp_eq_u32 s11, 28
	s_cselect_b32 s49, s5, s13
	s_cselect_b32 s48, s6, s12
	s_cselect_b32 s47, s7, s10
	s_cselect_b32 s46, s8, s9
	s_add_i32 s15, 0, 0x14000
	v_add_u32_e32 v154, s14, v163
	v_add_u32_e32 v158, s15, v163
	ds_read_b128 v[142:145], v154
	ds_read_b128 v[146:149], v154 offset:1024
	ds_read_b128 v[150:153], v154 offset:2048
	ds_read_b128 v[154:157], v154 offset:3072
	ds_read_b128 v[168:171], v158
	ds_read_b128 v[172:175], v158 offset:1024
	ds_read_b128 v[176:179], v158 offset:2048
	ds_read_b128 v[180:183], v158 offset:3072
	v_lshl_add_u64 v[158:159], s[44:45], 0, v[140:141]
	s_add_i32 m0, s60, 0xc000
	ds_read_b128 v[184:187], v167
	ds_read_b128 v[188:191], v167 offset:1024
	ds_read_b128 v[192:195], v167 offset:2048
	ds_read_b128 v[196:199], v167 offset:3072
	ds_read_b128 v[200:203], v167 offset:4096
	ds_read_b128 v[204:207], v167 offset:5120
	ds_read_b128 v[208:211], v167 offset:6144
	ds_read_b128 v[212:215], v167 offset:7168
	global_load_lds_dwordx4 v[158:159], off
	v_lshl_add_u64 v[158:159], s[44:45], 0, v[138:139]
	s_add_i32 m0, s60, 0xe000
	s_nop 0
	global_load_lds_dwordx4 v[158:159], off
	s_cmp_lg_u32 s32, 0
	s_cbranch_scc1 .Lgu_skip1
	s_waitcnt vmcnt(8)
.Lgu_skip1:
	s_waitcnt lgkmcnt(0)
	s_barrier
	s_setprio 1
	s_waitcnt lgkmcnt(0)
	v_mfma_f32_16x16x32_bf16 v[124:127], v[142:145], v[184:187], v[124:127]
	v_mfma_f32_16x16x32_bf16 v[120:123], v[150:153], v[184:187], v[120:123]
	v_mfma_f32_16x16x32_bf16 v[112:115], v[142:145], v[192:195], v[112:115]
	v_mfma_f32_16x16x32_bf16 v[104:107], v[150:153], v[192:195], v[104:107]
	v_mfma_f32_16x16x32_bf16 v[96:99], v[142:145], v[200:203], v[96:99]
	v_mfma_f32_16x16x32_bf16 v[88:91], v[150:153], v[200:203], v[88:91]
	v_mfma_f32_16x16x32_bf16 v[80:83], v[142:145], v[208:211], v[80:83]
	v_mfma_f32_16x16x32_bf16 v[72:75], v[150:153], v[208:211], v[72:75]
	v_mfma_f32_16x16x32_bf16 v[124:127], v[146:149], v[188:191], v[124:127]
	v_mfma_f32_16x16x32_bf16 v[120:123], v[154:157], v[188:191], v[120:123]
	v_mfma_f32_16x16x32_bf16 v[112:115], v[146:149], v[196:199], v[112:115]
	v_mfma_f32_16x16x32_bf16 v[104:107], v[154:157], v[196:199], v[104:107]
	v_mfma_f32_16x16x32_bf16 v[96:99], v[146:149], v[204:207], v[96:99]
	v_mfma_f32_16x16x32_bf16 v[88:91], v[154:157], v[204:207], v[88:91]
	v_mfma_f32_16x16x32_bf16 v[80:83], v[146:149], v[212:215], v[80:83]
	v_mfma_f32_16x16x32_bf16 v[72:75], v[154:157], v[212:215], v[72:75]
	s_setprio 0
	s_setprio 1
	v_mfma_f32_16x16x32_bf16 v[128:131], v[168:171], v[184:187], v[128:131]
	v_mfma_f32_16x16x32_bf16 v[116:119], v[176:179], v[184:187], v[116:119]
	v_mfma_f32_16x16x32_bf16 v[108:111], v[168:171], v[192:195], v[108:111]
	v_mfma_f32_16x16x32_bf16 v[100:103], v[176:179], v[192:195], v[100:103]
	v_mfma_f32_16x16x32_bf16 v[92:95], v[168:171], v[200:203], v[92:95]
	v_mfma_f32_16x16x32_bf16 v[84:87], v[176:179], v[200:203], v[84:87]
	v_mfma_f32_16x16x32_bf16 v[76:79], v[168:171], v[208:211], v[76:79]
	v_mfma_f32_16x16x32_bf16 v[68:71], v[176:179], v[208:211], v[68:71]
	v_mfma_f32_16x16x32_bf16 v[128:131], v[172:175], v[188:191], v[128:131]
	v_mfma_f32_16x16x32_bf16 v[116:119], v[180:183], v[188:191], v[116:119]
	v_mfma_f32_16x16x32_bf16 v[108:111], v[172:175], v[196:199], v[108:111]
	v_mfma_f32_16x16x32_bf16 v[100:103], v[180:183], v[196:199], v[100:103]
	v_mfma_f32_16x16x32_bf16 v[92:95], v[172:175], v[204:207], v[92:95]
	v_mfma_f32_16x16x32_bf16 v[84:87], v[180:183], v[204:207], v[84:87]
	v_mfma_f32_16x16x32_bf16 v[76:79], v[172:175], v[212:215], v[76:79]
	v_mfma_f32_16x16x32_bf16 v[68:71], v[180:183], v[212:215], v[68:71]
	s_setprio 0
	s_barrier
	s_add_i32 s12, s14, s56
	v_lshl_add_u64 v[158:159], s[46:47], 0, v[2:3]
	s_mov_b32 m0, s12
	ds_read_b128 v[184:187], v167 offset:16384
	ds_read_b128 v[188:191], v167 offset:17408
	ds_read_b128 v[192:195], v167 offset:18432
	ds_read_b128 v[196:199], v167 offset:19456
	ds_read_b128 v[200:203], v167 offset:20480
	ds_read_b128 v[204:207], v167 offset:21504
	ds_read_b128 v[208:211], v167 offset:22528
	ds_read_b128 v[212:215], v167 offset:23552
	global_load_lds_dwordx4 v[158:159], off
	s_add_i32 m0, s12, 0x2000
	s_add_u32 s12, s46, 0x80000
	v_lshl_add_u64 v[216:217], s[46:47], 0, v[0:1]
	s_addc_u32 s13, s47, 0
	s_add_i32 s14, s15, s56
	global_load_lds_dwordx4 v[216:217], off
	v_lshl_add_u64 v[218:219], s[12:13], 0, v[2:3]
	s_mov_b32 m0, s14
	v_lshl_add_u64 v[220:221], s[48:49], 0, v[132:133]
	global_load_lds_dwordx4 v[218:219], off
	v_lshl_add_u64 v[218:219], s[12:13], 0, v[0:1]
	s_add_i32 m0, s14, 0x2000
	s_nop 0
	global_load_lds_dwordx4 v[218:219], off
	v_lshl_add_u64 v[218:219], s[48:49], 0, v[134:135]
	s_mov_b32 m0, s60
	s_nop 0
	global_load_lds_dwordx4 v[218:219], off
	s_mov_b32 m0, s61
	s_nop 0
	global_load_lds_dwordx4 v[220:221], off
	s_cmp_lg_u32 s32, 0
	s_cbranch_scc1 .Lgu_skip2
	s_waitcnt vmcnt(8)
.Lgu_skip2:
	s_mov_b32 s32, 0
	s_waitcnt lgkmcnt(0)
	s_barrier
	s_setprio 1
	s_waitcnt lgkmcnt(0)
	v_mfma_f32_16x16x32_bf16 v[64:67], v[142:145], v[184:187], v[64:67]
	v_mfma_f32_16x16x32_bf16 v[56:59], v[150:153], v[184:187], v[56:59]
	v_mfma_f32_16x16x32_bf16 v[48:51], v[142:145], v[192:195], v[48:51]
	v_mfma_f32_16x16x32_bf16 v[40:43], v[150:153], v[192:195], v[40:43]
	v_mfma_f32_16x16x32_bf16 v[32:35], v[142:145], v[200:203], v[32:35]
	v_mfma_f32_16x16x32_bf16 v[24:27], v[150:153], v[200:203], v[24:27]
	v_mfma_f32_16x16x32_bf16 v[16:19], v[142:145], v[208:211], v[16:19]
	v_mfma_f32_16x16x32_bf16 v[8:11], v[150:153], v[208:211], v[8:11]
	v_mfma_f32_16x16x32_bf16 v[64:67], v[146:149], v[188:191], v[64:67]
	v_mfma_f32_16x16x32_bf16 v[56:59], v[154:157], v[188:191], v[56:59]
	v_mfma_f32_16x16x32_bf16 v[48:51], v[146:149], v[196:199], v[48:51]
	v_mfma_f32_16x16x32_bf16 v[40:43], v[154:157], v[196:199], v[40:43]
	v_mfma_f32_16x16x32_bf16 v[32:35], v[146:149], v[204:207], v[32:35]
	v_mfma_f32_16x16x32_bf16 v[24:27], v[154:157], v[204:207], v[24:27]
	v_mfma_f32_16x16x32_bf16 v[16:19], v[146:149], v[212:215], v[16:19]
	v_mfma_f32_16x16x32_bf16 v[8:11], v[154:157], v[212:215], v[8:11]
	s_setprio 0
	s_setprio 1
	v_mfma_f32_16x16x32_bf16 v[60:63], v[168:171], v[184:187], v[60:63]
	v_mfma_f32_16x16x32_bf16 v[52:55], v[176:179], v[184:187], v[52:55]
	v_mfma_f32_16x16x32_bf16 v[44:47], v[168:171], v[192:195], v[44:47]
	v_mfma_f32_16x16x32_bf16 v[36:39], v[176:179], v[192:195], v[36:39]
	v_mfma_f32_16x16x32_bf16 v[28:31], v[168:171], v[200:203], v[28:31]
	v_mfma_f32_16x16x32_bf16 v[20:23], v[176:179], v[200:203], v[20:23]
	v_mfma_f32_16x16x32_bf16 v[12:15], v[168:171], v[208:211], v[12:15]
	v_mfma_f32_16x16x32_bf16 v[4:7], v[176:179], v[208:211], v[4:7]
	v_mfma_f32_16x16x32_bf16 v[60:63], v[172:175], v[188:191], v[60:63]
	v_mfma_f32_16x16x32_bf16 v[52:55], v[180:183], v[188:191], v[52:55]
	v_mfma_f32_16x16x32_bf16 v[44:47], v[172:175], v[196:199], v[44:47]
	v_mfma_f32_16x16x32_bf16 v[36:39], v[180:183], v[196:199], v[36:39]
	v_mfma_f32_16x16x32_bf16 v[28:31], v[172:175], v[204:207], v[28:31]
	v_mfma_f32_16x16x32_bf16 v[20:23], v[180:183], v[204:207], v[20:23]
	v_mfma_f32_16x16x32_bf16 v[12:15], v[172:175], v[212:215], v[12:15]
	v_mfma_f32_16x16x32_bf16 v[4:7], v[180:183], v[212:215], v[4:7]
	s_setprio 0
	s_barrier
	s_add_i32 s14, 0, 0x18000
	s_add_i32 s15, 0, 0x1c000
	v_add_u32_e32 v154, s14, v163
	v_add_u32_e32 v160, s15, v163
	ds_read_b128 v[142:145], v154
	ds_read_b128 v[146:149], v154 offset:1024
	ds_read_b128 v[150:153], v154 offset:2048
	ds_read_b128 v[154:157], v154 offset:3072
	ds_read_b128 v[168:171], v160
	ds_read_b128 v[172:175], v160 offset:1024
	ds_read_b128 v[176:179], v160 offset:2048
	ds_read_b128 v[180:183], v160 offset:3072
	s_add_u32 s12, s48, 0x80000
	s_addc_u32 s13, s49, 0
	s_mov_b32 m0, s62
	v_lshl_add_u64 v[222:223], s[12:13], 0, v[134:135]
	ds_read_b128 v[184:187], v167 offset:32768
	ds_read_b128 v[188:191], v167 offset:33792
	ds_read_b128 v[192:195], v167 offset:34816
	ds_read_b128 v[196:199], v167 offset:35840
	ds_read_b128 v[200:203], v167 offset:36864
	ds_read_b128 v[204:207], v167 offset:37888
	ds_read_b128 v[208:211], v167 offset:38912
	ds_read_b128 v[212:215], v167 offset:39936
	global_load_lds_dwordx4 v[222:223], off
	v_lshl_add_u64 v[222:223], s[12:13], 0, v[132:133]
	s_mov_b32 m0, s63
	s_nop 0
	global_load_lds_dwordx4 v[222:223], off
	s_waitcnt vmcnt(8)
	s_waitcnt lgkmcnt(0)
	s_barrier
	s_setprio 1
	s_waitcnt lgkmcnt(0)
	v_mfma_f32_16x16x32_bf16 v[124:127], v[142:145], v[184:187], v[124:127]
	v_mfma_f32_16x16x32_bf16 v[120:123], v[150:153], v[184:187], v[120:123]
	v_mfma_f32_16x16x32_bf16 v[112:115], v[142:145], v[192:195], v[112:115]
	v_mfma_f32_16x16x32_bf16 v[104:107], v[150:153], v[192:195], v[104:107]
	v_mfma_f32_16x16x32_bf16 v[96:99], v[142:145], v[200:203], v[96:99]
	v_mfma_f32_16x16x32_bf16 v[88:91], v[150:153], v[200:203], v[88:91]
	v_mfma_f32_16x16x32_bf16 v[80:83], v[142:145], v[208:211], v[80:83]
	v_mfma_f32_16x16x32_bf16 v[72:75], v[150:153], v[208:211], v[72:75]
	v_mfma_f32_16x16x32_bf16 v[124:127], v[146:149], v[188:191], v[124:127]
	v_mfma_f32_16x16x32_bf16 v[120:123], v[154:157], v[188:191], v[120:123]
	v_mfma_f32_16x16x32_bf16 v[112:115], v[146:149], v[196:199], v[112:115]
	v_mfma_f32_16x16x32_bf16 v[104:107], v[154:157], v[196:199], v[104:107]
	v_mfma_f32_16x16x32_bf16 v[96:99], v[146:149], v[204:207], v[96:99]
	v_mfma_f32_16x16x32_bf16 v[88:91], v[154:157], v[204:207], v[88:91]
	v_mfma_f32_16x16x32_bf16 v[80:83], v[146:149], v[212:215], v[80:83]
	v_mfma_f32_16x16x32_bf16 v[72:75], v[154:157], v[212:215], v[72:75]
	s_setprio 0
	s_setprio 1
	v_mfma_f32_16x16x32_bf16 v[128:131], v[168:171], v[184:187], v[128:131]
	v_mfma_f32_16x16x32_bf16 v[116:119], v[176:179], v[184:187], v[116:119]
	v_mfma_f32_16x16x32_bf16 v[108:111], v[168:171], v[192:195], v[108:111]
	v_mfma_f32_16x16x32_bf16 v[100:103], v[176:179], v[192:195], v[100:103]
	v_mfma_f32_16x16x32_bf16 v[92:95], v[168:171], v[200:203], v[92:95]
	v_mfma_f32_16x16x32_bf16 v[84:87], v[176:179], v[200:203], v[84:87]
	v_mfma_f32_16x16x32_bf16 v[76:79], v[168:171], v[208:211], v[76:79]
	v_mfma_f32_16x16x32_bf16 v[68:71], v[176:179], v[208:211], v[68:71]
	v_mfma_f32_16x16x32_bf16 v[128:131], v[172:175], v[188:191], v[128:131]
	v_mfma_f32_16x16x32_bf16 v[116:119], v[180:183], v[188:191], v[116:119]
	v_mfma_f32_16x16x32_bf16 v[108:111], v[172:175], v[196:199], v[108:111]
	v_mfma_f32_16x16x32_bf16 v[100:103], v[180:183], v[196:199], v[100:103]
	v_mfma_f32_16x16x32_bf16 v[92:95], v[172:175], v[204:207], v[92:95]
	v_mfma_f32_16x16x32_bf16 v[84:87], v[180:183], v[204:207], v[84:87]
	v_mfma_f32_16x16x32_bf16 v[76:79], v[172:175], v[212:215], v[76:79]
	v_mfma_f32_16x16x32_bf16 v[68:71], v[180:183], v[212:215], v[68:71]
	s_setprio 0
	s_barrier
	s_add_i32 s12, s14, s56
	v_lshl_add_u64 v[158:159], v[158:159], 0, s[68:69]
	s_mov_b32 m0, s12
	ds_read_b128 v[184:187], v167 offset:49152
	ds_read_b128 v[188:191], v167 offset:50176
	ds_read_b128 v[192:195], v167 offset:51200
	ds_read_b128 v[196:199], v167 offset:52224
	ds_read_b128 v[200:203], v167 offset:53248
	ds_read_b128 v[204:207], v167 offset:54272
	ds_read_b128 v[208:211], v167 offset:55296
	ds_read_b128 v[212:215], v167 offset:56320
	global_load_lds_dwordx4 v[158:159], off
	s_add_i32 m0, s12, 0x2000
	s_add_u32 s12, s46, 0x80080
	v_lshl_add_u64 v[158:159], v[216:217], 0, s[68:69]
	s_addc_u32 s13, s47, 0
	s_add_i32 s14, s15, s56
	global_load_lds_dwordx4 v[158:159], off
	v_lshl_add_u64 v[158:159], s[12:13], 0, v[2:3]
	s_mov_b32 m0, s14
	s_nop 0
	global_load_lds_dwordx4 v[158:159], off
	v_lshl_add_u64 v[158:159], s[12:13], 0, v[0:1]
	s_add_i32 m0, s14, 0x2000
	s_nop 0
	global_load_lds_dwordx4 v[158:159], off
	v_lshl_add_u64 v[158:159], v[218:219], 0, s[68:69]
	s_mov_b32 m0, s64
	s_nop 0
	global_load_lds_dwordx4 v[158:159], off
	v_lshl_add_u64 v[158:159], v[220:221], 0, s[68:69]
	s_mov_b32 m0, s65
	s_nop 0
	global_load_lds_dwordx4 v[158:159], off
	s_waitcnt vmcnt(8)
	s_waitcnt lgkmcnt(0)
	s_barrier
	s_setprio 1
	s_waitcnt lgkmcnt(0)
	v_mfma_f32_16x16x32_bf16 v[64:67], v[142:145], v[184:187], v[64:67]
	v_mfma_f32_16x16x32_bf16 v[56:59], v[150:153], v[184:187], v[56:59]
	v_mfma_f32_16x16x32_bf16 v[48:51], v[142:145], v[192:195], v[48:51]
	v_mfma_f32_16x16x32_bf16 v[40:43], v[150:153], v[192:195], v[40:43]
	v_mfma_f32_16x16x32_bf16 v[32:35], v[142:145], v[200:203], v[32:35]
	v_mfma_f32_16x16x32_bf16 v[24:27], v[150:153], v[200:203], v[24:27]
	v_mfma_f32_16x16x32_bf16 v[16:19], v[142:145], v[208:211], v[16:19]
	v_mfma_f32_16x16x32_bf16 v[8:11], v[150:153], v[208:211], v[8:11]
	v_mfma_f32_16x16x32_bf16 v[64:67], v[146:149], v[188:191], v[64:67]
	v_mfma_f32_16x16x32_bf16 v[56:59], v[154:157], v[188:191], v[56:59]
	v_mfma_f32_16x16x32_bf16 v[48:51], v[146:149], v[196:199], v[48:51]
	v_mfma_f32_16x16x32_bf16 v[40:43], v[154:157], v[196:199], v[40:43]
	v_mfma_f32_16x16x32_bf16 v[32:35], v[146:149], v[204:207], v[32:35]
	v_mfma_f32_16x16x32_bf16 v[24:27], v[154:157], v[204:207], v[24:27]
	v_mfma_f32_16x16x32_bf16 v[16:19], v[146:149], v[212:215], v[16:19]
	v_mfma_f32_16x16x32_bf16 v[8:11], v[154:157], v[212:215], v[8:11]
	s_setprio 0
	s_setprio 1
	v_mfma_f32_16x16x32_bf16 v[60:63], v[168:171], v[184:187], v[60:63]
	v_mfma_f32_16x16x32_bf16 v[52:55], v[176:179], v[184:187], v[52:55]
	v_mfma_f32_16x16x32_bf16 v[44:47], v[168:171], v[192:195], v[44:47]
	v_mfma_f32_16x16x32_bf16 v[36:39], v[176:179], v[192:195], v[36:39]
	v_mfma_f32_16x16x32_bf16 v[28:31], v[168:171], v[200:203], v[28:31]
	v_mfma_f32_16x16x32_bf16 v[20:23], v[176:179], v[200:203], v[20:23]
	v_mfma_f32_16x16x32_bf16 v[12:15], v[168:171], v[208:211], v[12:15]
	v_mfma_f32_16x16x32_bf16 v[4:7], v[176:179], v[208:211], v[4:7]
	v_mfma_f32_16x16x32_bf16 v[60:63], v[172:175], v[188:191], v[60:63]
	v_mfma_f32_16x16x32_bf16 v[52:55], v[180:183], v[188:191], v[52:55]
	v_mfma_f32_16x16x32_bf16 v[44:47], v[172:175], v[196:199], v[44:47]
	v_mfma_f32_16x16x32_bf16 v[36:39], v[180:183], v[196:199], v[36:39]
	v_mfma_f32_16x16x32_bf16 v[28:31], v[172:175], v[204:207], v[28:31]
	v_mfma_f32_16x16x32_bf16 v[20:23], v[180:183], v[204:207], v[20:23]
	v_mfma_f32_16x16x32_bf16 v[12:15], v[172:175], v[212:215], v[12:15]
	v_mfma_f32_16x16x32_bf16 v[4:7], v[180:183], v[212:215], v[4:7]
	s_setprio 0
	s_barrier
	s_add_i32 s11, s11, 2
	s_add_u32 s9, s9, 0x100
	s_addc_u32 s10, s10, 0
	s_add_u32 s44, s44, 0x100
	s_addc_u32 s45, s45, 0
	s_cmp_gt_u32 s11, 29
	s_cbranch_scc0 .LBB0_1066
	s_and_b64 vcc, exec, s[22:23]
	s_cbranch_vccz .LBB0_1069
	s_barrier
.LBB0_1069:
	v_lshl_add_u32 v142, s42, 8, v161
	v_or_b32_e32 v143, 16, v142
	v_or_b32_e32 v144, 32, v142
	v_or_b32_e32 v145, 48, v142
	v_add_u32_e32 v146, 0x80, v142
	v_add_u32_e32 v147, 0x90, v142
	v_add_u32_e32 v148, 0xa0, v142
	v_add_u32_e32 v149, 0xb0, v142
	s_cmp_eq_u32 s42, s98
	s_cbranch_scc1 .Lgu_scales_ready
	s_mov_b32 s98, s42
	v_mad_u64_u32 v[186:187], s[6:7], v142, 32, v[136:137]
	v_mad_u64_u32 v[188:189], s[6:7], v143, 32, v[136:137]
	v_mad_u64_u32 v[190:191], s[6:7], v144, 32, v[136:137]
	v_mad_u64_u32 v[192:193], s[6:7], v145, 32, v[136:137]
	v_mad_u64_u32 v[194:195], s[6:7], v146, 32, v[136:137]
	v_mad_u64_u32 v[196:197], s[6:7], v147, 32, v[136:137]
	v_mad_u64_u32 v[198:199], s[6:7], v148, 32, v[136:137]
	v_mad_u64_u32 v[200:201], s[6:7], v149, 32, v[136:137]
	global_load_dwordx2 v[170:171], v[186:187], off
	global_load_dwordx2 v[172:173], v[188:189], off
	global_load_dwordx2 v[174:175], v[190:191], off
	global_load_dwordx2 v[176:177], v[192:193], off
	global_load_dwordx2 v[178:179], v[194:195], off
	global_load_dwordx2 v[180:181], v[196:197], off
	global_load_dwordx2 v[182:183], v[198:199], off
	global_load_dwordx2 v[184:185], v[200:201], off
	s_waitcnt vmcnt(0)
	v_add_f32_e32 v170, v170, v171
	v_add_f32_e32 v172, v172, v173
	v_add_f32_e32 v174, v174, v175
	v_add_f32_e32 v176, v176, v177
	v_add_f32_e32 v178, v178, v179
	v_add_f32_e32 v180, v180, v181
	v_add_f32_e32 v182, v182, v183
	v_add_f32_e32 v184, v184, v185
	ds_bpermute_b32 v171, v164, v170
	ds_bpermute_b32 v173, v164, v172
	ds_bpermute_b32 v175, v164, v174
	ds_bpermute_b32 v177, v164, v176
	ds_bpermute_b32 v179, v164, v178
	ds_bpermute_b32 v181, v164, v180
	ds_bpermute_b32 v183, v164, v182
	ds_bpermute_b32 v185, v164, v184
	s_waitcnt lgkmcnt(0)
	v_add_f32_e32 v170, v170, v171
	v_add_f32_e32 v172, v172, v173
	v_add_f32_e32 v174, v174, v175
	v_add_f32_e32 v176, v176, v177
	v_add_f32_e32 v178, v178, v179
	v_add_f32_e32 v180, v180, v181
	v_add_f32_e32 v182, v182, v183
	v_add_f32_e32 v184, v184, v185
	ds_bpermute_b32 v171, v165, v170
	ds_bpermute_b32 v173, v165, v172
	ds_bpermute_b32 v175, v165, v174
	ds_bpermute_b32 v177, v165, v176
	ds_bpermute_b32 v179, v165, v178
	ds_bpermute_b32 v181, v165, v180
	ds_bpermute_b32 v183, v165, v182
	ds_bpermute_b32 v185, v165, v184
	s_waitcnt lgkmcnt(0)
	v_add_f32_e32 v170, v170, v171
	v_add_f32_e32 v172, v172, v173
	v_add_f32_e32 v174, v174, v175
	v_add_f32_e32 v176, v176, v177
	v_add_f32_e32 v178, v178, v179
	v_add_f32_e32 v180, v180, v181
	v_add_f32_e32 v182, v182, v183
	v_add_f32_e32 v184, v184, v185
	v_fmamk_f32 v170, v170, 0x3a000000, v232
	v_fmamk_f32 v172, v172, 0x3a000000, v232
	v_fmamk_f32 v174, v174, 0x3a000000, v232
	v_fmamk_f32 v176, v176, 0x3a000000, v232
	v_fmamk_f32 v178, v178, 0x3a000000, v232
	v_fmamk_f32 v180, v180, 0x3a000000, v232
	v_fmamk_f32 v182, v182, 0x3a000000, v232
	v_fmamk_f32 v184, v184, 0x3a000000, v232
	v_rsq_f32_e32 v228, v170
	v_rsq_f32_e32 v230, v172
	v_rsq_f32_e32 v238, v174
	v_rsq_f32_e32 v242, v176
	v_rsq_f32_e32 v244, v178
	v_rsq_f32_e32 v246, v180
	v_rsq_f32_e32 v248, v182
	v_rsq_f32_e32 v250, v184
	s_nop 0
.Lgu_scales_ready:
	v_lshl_or_b32 v158, s4, 7, v166
	v_ashrrev_i32_e32 v159, 31, v158
	v_lshlrev_b64 v[158:159], 1, v[158:159]
	v_mov_b64_e32 v[154:155], s[20:21]
	s_movk_i32 s6, 0x2c00
	v_mad_i64_i32 v[202:203], s[4:5], v142, s6, v[154:155]
	v_mad_i64_i32 v[204:205], s[4:5], v143, s6, v[154:155]
	v_mad_i64_i32 v[206:207], s[4:5], v144, s6, v[154:155]
	v_mad_i64_i32 v[208:209], s[4:5], v145, s6, v[154:155]
	v_mad_i64_i32 v[210:211], s[4:5], v146, s6, v[154:155]
	v_mad_i64_i32 v[212:213], s[4:5], v147, s6, v[154:155]
	v_mad_i64_i32 v[214:215], s[4:5], v148, s6, v[154:155]
	v_mad_i64_i32 v[216:217], s[4:5], v149, s6, v[154:155]
	v_lshl_add_u64 v[202:203], v[202:203], 0, v[158:159]
	v_lshl_add_u64 v[204:205], v[204:205], 0, v[158:159]
	v_lshl_add_u64 v[206:207], v[206:207], 0, v[158:159]
	v_lshl_add_u64 v[208:209], v[208:209], 0, v[158:159]
	v_lshl_add_u64 v[210:211], v[210:211], 0, v[158:159]
	v_lshl_add_u64 v[212:213], v[212:213], 0, v[158:159]
	v_lshl_add_u64 v[214:215], v[214:215], 0, v[158:159]
	v_lshl_add_u64 v[216:217], v[216:217], 0, v[158:159]
	s_mov_b64 s[42:43], -1
	s_andn2_b64 vcc, exec, s[36:37]
	v_mul_f32_e32 v150, v228, v228
	v_mul_f32_e32 v152, 0xbfb8aa3b, v228
	v_pk_mul_f32 v[218:219], v[124:125], v[152:153] op_sel_hi:[1,0]
	v_pk_mul_f32 v[220:221], v[126:127], v[152:153] op_sel_hi:[1,0]
	v_pk_mul_f32 v[222:223], v[120:121], v[152:153] op_sel_hi:[1,0]
	v_pk_mul_f32 v[224:225], v[122:123], v[152:153] op_sel_hi:[1,0]
	v_exp_f32_e32 v218, v218
	v_exp_f32_e32 v219, v219
	v_exp_f32_e32 v220, v220
	v_exp_f32_e32 v221, v221
	v_exp_f32_e32 v222, v222
	v_exp_f32_e32 v223, v223
	v_exp_f32_e32 v224, v224
	v_exp_f32_e32 v225, v225
	v_pk_add_f32 v[218:219], v[218:219], 1.0 op_sel_hi:[1,0]
	v_pk_add_f32 v[220:221], v[220:221], 1.0 op_sel_hi:[1,0]
	v_pk_add_f32 v[222:223], v[222:223], 1.0 op_sel_hi:[1,0]
	v_pk_add_f32 v[224:225], v[224:225], 1.0 op_sel_hi:[1,0]
	v_rcp_f32_e32 v218, v218
	v_rcp_f32_e32 v219, v219
	v_rcp_f32_e32 v220, v220
	v_rcp_f32_e32 v221, v221
	v_rcp_f32_e32 v222, v222
	v_rcp_f32_e32 v223, v223
	v_rcp_f32_e32 v224, v224
	v_rcp_f32_e32 v225, v225
	v_pk_mul_f32 v[124:125], v[124:125], v[128:129]
	v_pk_mul_f32 v[126:127], v[126:127], v[130:131]
	v_pk_mul_f32 v[120:121], v[120:121], v[116:117]
	v_pk_mul_f32 v[122:123], v[122:123], v[118:119]
	v_pk_mul_f32 v[124:125], v[124:125], v[150:151] op_sel_hi:[1,0]
	v_pk_mul_f32 v[126:127], v[126:127], v[150:151] op_sel_hi:[1,0]
	v_pk_mul_f32 v[120:121], v[120:121], v[150:151] op_sel_hi:[1,0]
	v_pk_mul_f32 v[122:123], v[122:123], v[150:151] op_sel_hi:[1,0]
	v_pk_mul_f32 v[124:125], v[124:125], v[218:219]
	v_pk_mul_f32 v[126:127], v[126:127], v[220:221]
	v_pk_mul_f32 v[120:121], v[120:121], v[222:223]
	v_pk_mul_f32 v[122:123], v[122:123], v[224:225]
	v_cvt_pk_bf16_f32 v124, v124, v125
	v_cvt_pk_bf16_f32 v125, v126, v127
	v_cvt_pk_bf16_f32 v126, v120, v121
	v_cvt_pk_bf16_f32 v127, v122, v123
	s_waitcnt vmcnt(0)
	global_store_dwordx4 v[202:203], v[124:127], off
	v_mul_f32_e32 v150, v230, v230
	v_mul_f32_e32 v152, 0xbfb8aa3b, v230
	v_pk_mul_f32 v[218:219], v[112:113], v[152:153] op_sel_hi:[1,0]
	v_pk_mul_f32 v[220:221], v[114:115], v[152:153] op_sel_hi:[1,0]
	v_pk_mul_f32 v[222:223], v[104:105], v[152:153] op_sel_hi:[1,0]
	v_pk_mul_f32 v[224:225], v[106:107], v[152:153] op_sel_hi:[1,0]
	v_exp_f32_e32 v218, v218
	v_exp_f32_e32 v219, v219
	v_exp_f32_e32 v220, v220
	v_exp_f32_e32 v221, v221
	v_exp_f32_e32 v222, v222
	v_exp_f32_e32 v223, v223
	v_exp_f32_e32 v224, v224
	v_exp_f32_e32 v225, v225
	v_pk_add_f32 v[218:219], v[218:219], 1.0 op_sel_hi:[1,0]
	v_pk_add_f32 v[220:221], v[220:221], 1.0 op_sel_hi:[1,0]
	v_pk_add_f32 v[222:223], v[222:223], 1.0 op_sel_hi:[1,0]
	v_pk_add_f32 v[224:225], v[224:225], 1.0 op_sel_hi:[1,0]
	v_rcp_f32_e32 v218, v218
	v_rcp_f32_e32 v219, v219
	v_rcp_f32_e32 v220, v220
	v_rcp_f32_e32 v221, v221
	v_rcp_f32_e32 v222, v222
	v_rcp_f32_e32 v223, v223
	v_rcp_f32_e32 v224, v224
	v_rcp_f32_e32 v225, v225
	v_pk_mul_f32 v[112:113], v[112:113], v[108:109]
	v_pk_mul_f32 v[114:115], v[114:115], v[110:111]
	v_pk_mul_f32 v[104:105], v[104:105], v[100:101]
	v_pk_mul_f32 v[106:107], v[106:107], v[102:103]
	v_pk_mul_f32 v[112:113], v[112:113], v[150:151] op_sel_hi:[1,0]
	v_pk_mul_f32 v[114:115], v[114:115], v[150:151] op_sel_hi:[1,0]
	v_pk_mul_f32 v[104:105], v[104:105], v[150:151] op_sel_hi:[1,0]
	v_pk_mul_f32 v[106:107], v[106:107], v[150:151] op_sel_hi:[1,0]
	v_pk_mul_f32 v[112:113], v[112:113], v[218:219]
	v_pk_mul_f32 v[114:115], v[114:115], v[220:221]
	v_pk_mul_f32 v[104:105], v[104:105], v[222:223]
	v_pk_mul_f32 v[106:107], v[106:107], v[224:225]
	v_cvt_pk_bf16_f32 v112, v112, v113
	v_cvt_pk_bf16_f32 v113, v114, v115
	v_cvt_pk_bf16_f32 v114, v104, v105
	v_cvt_pk_bf16_f32 v115, v106, v107
	global_store_dwordx4 v[204:205], v[112:115], off
	v_mul_f32_e32 v150, v238, v238
	v_mul_f32_e32 v152, 0xbfb8aa3b, v238
	v_pk_mul_f32 v[218:219], v[96:97], v[152:153] op_sel_hi:[1,0]
	v_pk_mul_f32 v[220:221], v[98:99], v[152:153] op_sel_hi:[1,0]
	v_pk_mul_f32 v[222:223], v[88:89], v[152:153] op_sel_hi:[1,0]
	v_pk_mul_f32 v[224:225], v[90:91], v[152:153] op_sel_hi:[1,0]
	v_exp_f32_e32 v218, v218
	v_exp_f32_e32 v219, v219
	v_exp_f32_e32 v220, v220
	v_exp_f32_e32 v221, v221
	v_exp_f32_e32 v222, v222
	v_exp_f32_e32 v223, v223
	v_exp_f32_e32 v224, v224
	v_exp_f32_e32 v225, v225
	v_pk_add_f32 v[218:219], v[218:219], 1.0 op_sel_hi:[1,0]
	v_pk_add_f32 v[220:221], v[220:221], 1.0 op_sel_hi:[1,0]
	v_pk_add_f32 v[222:223], v[222:223], 1.0 op_sel_hi:[1,0]
	v_pk_add_f32 v[224:225], v[224:225], 1.0 op_sel_hi:[1,0]
	v_rcp_f32_e32 v218, v218
	v_rcp_f32_e32 v219, v219
	v_rcp_f32_e32 v220, v220
	v_rcp_f32_e32 v221, v221
	v_rcp_f32_e32 v222, v222
	v_rcp_f32_e32 v223, v223
	v_rcp_f32_e32 v224, v224
	v_rcp_f32_e32 v225, v225
	v_pk_mul_f32 v[96:97], v[96:97], v[92:93]
	v_pk_mul_f32 v[98:99], v[98:99], v[94:95]
	v_pk_mul_f32 v[88:89], v[88:89], v[84:85]
	v_pk_mul_f32 v[90:91], v[90:91], v[86:87]
	v_pk_mul_f32 v[96:97], v[96:97], v[150:151] op_sel_hi:[1,0]
	v_pk_mul_f32 v[98:99], v[98:99], v[150:151] op_sel_hi:[1,0]
	v_pk_mul_f32 v[88:89], v[88:89], v[150:151] op_sel_hi:[1,0]
	v_pk_mul_f32 v[90:91], v[90:91], v[150:151] op_sel_hi:[1,0]
	v_pk_mul_f32 v[96:97], v[96:97], v[218:219]
	v_pk_mul_f32 v[98:99], v[98:99], v[220:221]
	v_pk_mul_f32 v[88:89], v[88:89], v[222:223]
	v_pk_mul_f32 v[90:91], v[90:91], v[224:225]
	v_cvt_pk_bf16_f32 v96, v96, v97
	v_cvt_pk_bf16_f32 v97, v98, v99
	v_cvt_pk_bf16_f32 v98, v88, v89
	v_cvt_pk_bf16_f32 v99, v90, v91
	global_store_dwordx4 v[206:207], v[96:99], off
	v_mul_f32_e32 v150, v242, v242
	v_mul_f32_e32 v152, 0xbfb8aa3b, v242
	v_pk_mul_f32 v[218:219], v[80:81], v[152:153] op_sel_hi:[1,0]
	v_pk_mul_f32 v[220:221], v[82:83], v[152:153] op_sel_hi:[1,0]
	v_pk_mul_f32 v[222:223], v[72:73], v[152:153] op_sel_hi:[1,0]
	v_pk_mul_f32 v[224:225], v[74:75], v[152:153] op_sel_hi:[1,0]
	v_exp_f32_e32 v218, v218
	v_exp_f32_e32 v219, v219
	v_exp_f32_e32 v220, v220
	v_exp_f32_e32 v221, v221
	v_exp_f32_e32 v222, v222
	v_exp_f32_e32 v223, v223
	v_exp_f32_e32 v224, v224
	v_exp_f32_e32 v225, v225
	v_pk_add_f32 v[218:219], v[218:219], 1.0 op_sel_hi:[1,0]
	v_pk_add_f32 v[220:221], v[220:221], 1.0 op_sel_hi:[1,0]
	v_pk_add_f32 v[222:223], v[222:223], 1.0 op_sel_hi:[1,0]
	v_pk_add_f32 v[224:225], v[224:225], 1.0 op_sel_hi:[1,0]
	v_rcp_f32_e32 v218, v218
	v_rcp_f32_e32 v219, v219
	v_rcp_f32_e32 v220, v220
	v_rcp_f32_e32 v221, v221
	v_rcp_f32_e32 v222, v222
	v_rcp_f32_e32 v223, v223
	v_rcp_f32_e32 v224, v224
	v_rcp_f32_e32 v225, v225
	v_pk_mul_f32 v[80:81], v[80:81], v[76:77]
	v_pk_mul_f32 v[82:83], v[82:83], v[78:79]
	v_pk_mul_f32 v[72:73], v[72:73], v[68:69]
	v_pk_mul_f32 v[74:75], v[74:75], v[70:71]
	v_pk_mul_f32 v[80:81], v[80:81], v[150:151] op_sel_hi:[1,0]
	v_pk_mul_f32 v[82:83], v[82:83], v[150:151] op_sel_hi:[1,0]
	v_pk_mul_f32 v[72:73], v[72:73], v[150:151] op_sel_hi:[1,0]
	v_pk_mul_f32 v[74:75], v[74:75], v[150:151] op_sel_hi:[1,0]
	v_pk_mul_f32 v[80:81], v[80:81], v[218:219]
	v_pk_mul_f32 v[82:83], v[82:83], v[220:221]
	v_pk_mul_f32 v[72:73], v[72:73], v[222:223]
	v_pk_mul_f32 v[74:75], v[74:75], v[224:225]
	v_cvt_pk_bf16_f32 v80, v80, v81
	v_cvt_pk_bf16_f32 v81, v82, v83
	v_cvt_pk_bf16_f32 v82, v72, v73
	v_cvt_pk_bf16_f32 v83, v74, v75
	global_store_dwordx4 v[208:209], v[80:83], off
	v_mul_f32_e32 v150, v244, v244
	v_mul_f32_e32 v152, 0xbfb8aa3b, v244
	v_pk_mul_f32 v[218:219], v[64:65], v[152:153] op_sel_hi:[1,0]
	v_pk_mul_f32 v[220:221], v[66:67], v[152:153] op_sel_hi:[1,0]
	v_pk_mul_f32 v[222:223], v[56:57], v[152:153] op_sel_hi:[1,0]
	v_pk_mul_f32 v[224:225], v[58:59], v[152:153] op_sel_hi:[1,0]
	v_exp_f32_e32 v218, v218
	v_exp_f32_e32 v219, v219
	v_exp_f32_e32 v220, v220
	v_exp_f32_e32 v221, v221
	v_exp_f32_e32 v222, v222
	v_exp_f32_e32 v223, v223
	v_exp_f32_e32 v224, v224
	v_exp_f32_e32 v225, v225
	v_pk_add_f32 v[218:219], v[218:219], 1.0 op_sel_hi:[1,0]
	v_pk_add_f32 v[220:221], v[220:221], 1.0 op_sel_hi:[1,0]
	v_pk_add_f32 v[222:223], v[222:223], 1.0 op_sel_hi:[1,0]
	v_pk_add_f32 v[224:225], v[224:225], 1.0 op_sel_hi:[1,0]
	v_rcp_f32_e32 v218, v218
	v_rcp_f32_e32 v219, v219
	v_rcp_f32_e32 v220, v220
	v_rcp_f32_e32 v221, v221
	v_rcp_f32_e32 v222, v222
	v_rcp_f32_e32 v223, v223
	v_rcp_f32_e32 v224, v224
	v_rcp_f32_e32 v225, v225
	v_pk_mul_f32 v[64:65], v[64:65], v[60:61]
	v_pk_mul_f32 v[66:67], v[66:67], v[62:63]
	v_pk_mul_f32 v[56:57], v[56:57], v[52:53]
	v_pk_mul_f32 v[58:59], v[58:59], v[54:55]
	v_pk_mul_f32 v[64:65], v[64:65], v[150:151] op_sel_hi:[1,0]
	v_pk_mul_f32 v[66:67], v[66:67], v[150:151] op_sel_hi:[1,0]
	v_pk_mul_f32 v[56:57], v[56:57], v[150:151] op_sel_hi:[1,0]
	v_pk_mul_f32 v[58:59], v[58:59], v[150:151] op_sel_hi:[1,0]
	v_pk_mul_f32 v[64:65], v[64:65], v[218:219]
	v_pk_mul_f32 v[66:67], v[66:67], v[220:221]
	v_pk_mul_f32 v[56:57], v[56:57], v[222:223]
	v_pk_mul_f32 v[58:59], v[58:59], v[224:225]
	v_cvt_pk_bf16_f32 v64, v64, v65
	v_cvt_pk_bf16_f32 v65, v66, v67
	v_cvt_pk_bf16_f32 v66, v56, v57
	v_cvt_pk_bf16_f32 v67, v58, v59
	global_store_dwordx4 v[210:211], v[64:67], off
	v_mul_f32_e32 v150, v246, v246
	v_mul_f32_e32 v152, 0xbfb8aa3b, v246
	v_pk_mul_f32 v[218:219], v[48:49], v[152:153] op_sel_hi:[1,0]
	v_pk_mul_f32 v[220:221], v[50:51], v[152:153] op_sel_hi:[1,0]
	v_pk_mul_f32 v[222:223], v[40:41], v[152:153] op_sel_hi:[1,0]
	v_pk_mul_f32 v[224:225], v[42:43], v[152:153] op_sel_hi:[1,0]
	v_exp_f32_e32 v218, v218
	v_exp_f32_e32 v219, v219
	v_exp_f32_e32 v220, v220
	v_exp_f32_e32 v221, v221
	v_exp_f32_e32 v222, v222
	v_exp_f32_e32 v223, v223
	v_exp_f32_e32 v224, v224
	v_exp_f32_e32 v225, v225
	v_pk_add_f32 v[218:219], v[218:219], 1.0 op_sel_hi:[1,0]
	v_pk_add_f32 v[220:221], v[220:221], 1.0 op_sel_hi:[1,0]
	v_pk_add_f32 v[222:223], v[222:223], 1.0 op_sel_hi:[1,0]
	v_pk_add_f32 v[224:225], v[224:225], 1.0 op_sel_hi:[1,0]
	v_rcp_f32_e32 v218, v218
	v_rcp_f32_e32 v219, v219
	v_rcp_f32_e32 v220, v220
	v_rcp_f32_e32 v221, v221
	v_rcp_f32_e32 v222, v222
	v_rcp_f32_e32 v223, v223
	v_rcp_f32_e32 v224, v224
	v_rcp_f32_e32 v225, v225
	v_pk_mul_f32 v[48:49], v[48:49], v[44:45]
	v_pk_mul_f32 v[50:51], v[50:51], v[46:47]
	v_pk_mul_f32 v[40:41], v[40:41], v[36:37]
	v_pk_mul_f32 v[42:43], v[42:43], v[38:39]
	v_pk_mul_f32 v[48:49], v[48:49], v[150:151] op_sel_hi:[1,0]
	v_pk_mul_f32 v[50:51], v[50:51], v[150:151] op_sel_hi:[1,0]
	v_pk_mul_f32 v[40:41], v[40:41], v[150:151] op_sel_hi:[1,0]
	v_pk_mul_f32 v[42:43], v[42:43], v[150:151] op_sel_hi:[1,0]
	v_pk_mul_f32 v[48:49], v[48:49], v[218:219]
	v_pk_mul_f32 v[50:51], v[50:51], v[220:221]
	v_pk_mul_f32 v[40:41], v[40:41], v[222:223]
	v_pk_mul_f32 v[42:43], v[42:43], v[224:225]
	v_cvt_pk_bf16_f32 v48, v48, v49
	v_cvt_pk_bf16_f32 v49, v50, v51
	v_cvt_pk_bf16_f32 v50, v40, v41
	v_cvt_pk_bf16_f32 v51, v42, v43
	global_store_dwordx4 v[212:213], v[48:51], off
	v_mul_f32_e32 v150, v248, v248
	v_mul_f32_e32 v152, 0xbfb8aa3b, v248
	v_pk_mul_f32 v[218:219], v[32:33], v[152:153] op_sel_hi:[1,0]
	v_pk_mul_f32 v[220:221], v[34:35], v[152:153] op_sel_hi:[1,0]
	v_pk_mul_f32 v[222:223], v[24:25], v[152:153] op_sel_hi:[1,0]
	v_pk_mul_f32 v[224:225], v[26:27], v[152:153] op_sel_hi:[1,0]
	v_exp_f32_e32 v218, v218
	v_exp_f32_e32 v219, v219
	v_exp_f32_e32 v220, v220
	v_exp_f32_e32 v221, v221
	v_exp_f32_e32 v222, v222
	v_exp_f32_e32 v223, v223
	v_exp_f32_e32 v224, v224
	v_exp_f32_e32 v225, v225
	v_pk_add_f32 v[218:219], v[218:219], 1.0 op_sel_hi:[1,0]
	v_pk_add_f32 v[220:221], v[220:221], 1.0 op_sel_hi:[1,0]
	v_pk_add_f32 v[222:223], v[222:223], 1.0 op_sel_hi:[1,0]
	v_pk_add_f32 v[224:225], v[224:225], 1.0 op_sel_hi:[1,0]
	v_rcp_f32_e32 v218, v218
	v_rcp_f32_e32 v219, v219
	v_rcp_f32_e32 v220, v220
	v_rcp_f32_e32 v221, v221
	v_rcp_f32_e32 v222, v222
	v_rcp_f32_e32 v223, v223
	v_rcp_f32_e32 v224, v224
	v_rcp_f32_e32 v225, v225
	v_pk_mul_f32 v[32:33], v[32:33], v[28:29]
	v_pk_mul_f32 v[34:35], v[34:35], v[30:31]
	v_pk_mul_f32 v[24:25], v[24:25], v[20:21]
	v_pk_mul_f32 v[26:27], v[26:27], v[22:23]
	v_pk_mul_f32 v[32:33], v[32:33], v[150:151] op_sel_hi:[1,0]
	v_pk_mul_f32 v[34:35], v[34:35], v[150:151] op_sel_hi:[1,0]
	v_pk_mul_f32 v[24:25], v[24:25], v[150:151] op_sel_hi:[1,0]
	v_pk_mul_f32 v[26:27], v[26:27], v[150:151] op_sel_hi:[1,0]
	v_pk_mul_f32 v[32:33], v[32:33], v[218:219]
	v_pk_mul_f32 v[34:35], v[34:35], v[220:221]
	v_pk_mul_f32 v[24:25], v[24:25], v[222:223]
	v_pk_mul_f32 v[26:27], v[26:27], v[224:225]
	v_cvt_pk_bf16_f32 v32, v32, v33
	v_cvt_pk_bf16_f32 v33, v34, v35
	v_cvt_pk_bf16_f32 v34, v24, v25
	v_cvt_pk_bf16_f32 v35, v26, v27
	global_store_dwordx4 v[214:215], v[32:35], off
	v_mul_f32_e32 v150, v250, v250
	v_mul_f32_e32 v152, 0xbfb8aa3b, v250
	v_pk_mul_f32 v[218:219], v[16:17], v[152:153] op_sel_hi:[1,0]
	v_pk_mul_f32 v[220:221], v[18:19], v[152:153] op_sel_hi:[1,0]
	v_pk_mul_f32 v[222:223], v[8:9], v[152:153] op_sel_hi:[1,0]
	v_pk_mul_f32 v[224:225], v[10:11], v[152:153] op_sel_hi:[1,0]
	v_exp_f32_e32 v218, v218
	v_exp_f32_e32 v219, v219
	v_exp_f32_e32 v220, v220
	v_exp_f32_e32 v221, v221
	v_exp_f32_e32 v222, v222
	v_exp_f32_e32 v223, v223
	v_exp_f32_e32 v224, v224
	v_exp_f32_e32 v225, v225
	v_pk_add_f32 v[218:219], v[218:219], 1.0 op_sel_hi:[1,0]
	v_pk_add_f32 v[220:221], v[220:221], 1.0 op_sel_hi:[1,0]
	v_pk_add_f32 v[222:223], v[222:223], 1.0 op_sel_hi:[1,0]
	v_pk_add_f32 v[224:225], v[224:225], 1.0 op_sel_hi:[1,0]
	v_rcp_f32_e32 v218, v218
	v_rcp_f32_e32 v219, v219
	v_rcp_f32_e32 v220, v220
	v_rcp_f32_e32 v221, v221
	v_rcp_f32_e32 v222, v222
	v_rcp_f32_e32 v223, v223
	v_rcp_f32_e32 v224, v224
	v_rcp_f32_e32 v225, v225
	v_pk_mul_f32 v[16:17], v[16:17], v[12:13]
	v_pk_mul_f32 v[18:19], v[18:19], v[14:15]
	v_pk_mul_f32 v[8:9], v[8:9], v[4:5]
	v_pk_mul_f32 v[10:11], v[10:11], v[6:7]
	v_pk_mul_f32 v[16:17], v[16:17], v[150:151] op_sel_hi:[1,0]
	v_pk_mul_f32 v[18:19], v[18:19], v[150:151] op_sel_hi:[1,0]
	v_pk_mul_f32 v[8:9], v[8:9], v[150:151] op_sel_hi:[1,0]
	v_pk_mul_f32 v[10:11], v[10:11], v[150:151] op_sel_hi:[1,0]
	v_pk_mul_f32 v[16:17], v[16:17], v[218:219]
	v_pk_mul_f32 v[18:19], v[18:19], v[220:221]
	v_pk_mul_f32 v[8:9], v[8:9], v[222:223]
	v_pk_mul_f32 v[10:11], v[10:11], v[224:225]
	v_cvt_pk_bf16_f32 v16, v16, v17
	v_cvt_pk_bf16_f32 v17, v18, v19
	v_cvt_pk_bf16_f32 v18, v8, v9
	v_cvt_pk_bf16_f32 v19, v10, v11
	global_store_dwordx4 v[216:217], v[16:19], off
	s_cbranch_vccnz .LBB0_1062
	s_andn2_b64 vcc, exec, s[2:3]
	s_cbranch_vccnz .LBB0_1061
	s_barrier
	s_branch .LBB0_1061

.LBB0_1306:
	v_readlane_b32 s2, v254, 17
	v_readlane_b32 s3, v254, 18
	v_cvt_f32_u32_e32 v1, v2
	v_sub_u32_e32 v5, 0, v2
	v_rcp_iflag_f32_e32 v1, v1
	s_nop 1
	global_atomic_add v4, v3, v233, s[2:3] sc0
	v_mul_f32_e32 v1, 0x4f7ffffe, v1
	v_cvt_u32_f32_e32 v1, v1
	v_mul_lo_u32 v5, v5, v1
	v_mul_hi_u32 v5, v1, v5
	v_add_u32_e32 v1, v1, v5
	s_waitcnt vmcnt(0)
	v_mul_hi_u32 v1, v4, v1
	v_mul_lo_u32 v5, v1, v2
	v_sub_u32_e32 v5, v4, v5
	v_add_u32_e32 v6, 1, v1
	v_cmp_ge_u32_e32 vcc, v5, v2
	v_add_u32_e32 v4, 1, v4
	s_nop 0
	v_cndmask_b32_e32 v1, v1, v6, vcc
	v_sub_u32_e32 v6, v5, v2
	v_cndmask_b32_e32 v5, v5, v6, vcc
	v_add_u32_e32 v6, 1, v1
	v_cmp_ge_u32_e32 vcc, v5, v2
	s_nop 1
	v_cndmask_b32_e32 v1, v1, v6, vcc
	v_mul_lo_u32 v5, v2, v1
	v_add_u32_e32 v2, v5, v2
	v_cmp_ne_u32_e32 vcc, v4, v2
	s_and_saveexec_b64 s[2:3], vcc
	s_xor_b64 s[2:3], exec, s[2:3]
	s_cbranch_execz .LBB0_1320
	v_readlane_b32 s4, v254, 19
	v_readlane_b32 s5, v254, 20
	s_waitcnt lgkmcnt(0)
	s_nop 3
	buffer_inv sc1
	global_load_dword v0, v3, s[4:5] sc1
	s_waitcnt vmcnt(0)
	v_cmp_eq_u32_e32 vcc, v0, v1
	s_and_saveexec_b64 s[20:21], vcc
	s_cbranch_execz .LBB0_1319
	s_mov_b32 s4, 1
	s_mov_b64 s[22:23], 0
	s_branch .LBB0_1310

.LBB0_1319:
	s_or_b64 exec, exec, s[20:21]
	s_waitcnt vmcnt(0)
	s_waitcnt vmcnt(0)

	.amdhsa_kernel _Z5k_fwd6Params
		.amdhsa_group_segment_fixed_size 0
		.amdhsa_private_segment_fixed_size 0
		.amdhsa_kernarg_size 384
		.amdhsa_user_sgpr_count 2
		.amdhsa_user_sgpr_dispatch_ptr 0
		.amdhsa_user_sgpr_queue_ptr 0
		.amdhsa_user_sgpr_kernarg_segment_ptr 1
		.amdhsa_user_sgpr_dispatch_id 0
		.amdhsa_user_sgpr_kernarg_preload_length 0
		.amdhsa_user_sgpr_kernarg_preload_offset 0
		.amdhsa_user_sgpr_private_segment_size 0
		.amdhsa_uses_dynamic_stack 0
		.amdhsa_enable_private_segment 0
		.amdhsa_system_sgpr_workgroup_id_x 1
		.amdhsa_system_sgpr_workgroup_id_y 0
		.amdhsa_system_sgpr_workgroup_id_z 0
		.amdhsa_system_sgpr_workgroup_info 0
		.amdhsa_system_vgpr_workitem_id 0
		.amdhsa_next_free_vgpr 256
		.amdhsa_next_free_sgpr 100
		.amdhsa_accum_offset 256
		.amdhsa_reserve_vcc 1
		.amdhsa_float_round_mode_32 0
		.amdhsa_float_round_mode_16_64 0
		.amdhsa_float_denorm_mode_32 3
		.amdhsa_float_denorm_mode_16_64 3
		.amdhsa_dx10_clamp 1
		.amdhsa_ieee_mode 1
		.amdhsa_fp16_overflow 0
		.amdhsa_tg_split 0
		.amdhsa_exception_fp_ieee_invalid_op 0
		.amdhsa_exception_fp_denorm_src 0
		.amdhsa_exception_fp_ieee_div_zero 0
		.amdhsa_exception_fp_ieee_overflow 0
		.amdhsa_exception_fp_ieee_underflow 0
		.amdhsa_exception_fp_ieee_inexact 0
		.amdhsa_exception_int_div_zero 0
	.end_amdhsa_kernel

amdhsa.kernels:
  - .agpr_count:     0
    .args:
      - .offset:         0
        .size:           128
        .value_kind:     by_value
      - .offset:         128
        .size:           4
        .value_kind:     hidden_block_count_x
      - .offset:         132
        .size:           4
        .value_kind:     hidden_block_count_y
      - .offset:         136
        .size:           4
        .value_kind:     hidden_block_count_z
      - .offset:         140
        .size:           2
        .value_kind:     hidden_group_size_x
      - .offset:         142
        .size:           2
        .value_kind:     hidden_group_size_y
      - .offset:         144
        .size:           2
        .value_kind:     hidden_group_size_z
      - .offset:         146
        .size:           2
        .value_kind:     hidden_remainder_x
      - .offset:         148
        .size:           2
        .value_kind:     hidden_remainder_y
      - .offset:         150
        .size:           2
        .value_kind:     hidden_remainder_z
      - .offset:         168
        .size:           8
        .value_kind:     hidden_global_offset_x
      - .offset:         176
        .size:           8
        .value_kind:     hidden_global_offset_y
      - .offset:         184
        .size:           8
        .value_kind:     hidden_global_offset_z
      - .offset:         192
        .size:           2
        .value_kind:     hidden_grid_dims
      - .offset:         248
        .size:           4
        .value_kind:     hidden_dynamic_lds_size
    .group_segment_fixed_size: 0
    .kernarg_segment_align: 8
    .kernarg_segment_size: 384
    .language:       OpenCL C
    .language_version:
      - 2
      - 0
    .max_flat_workgroup_size: 512
    .name:           _Z5k_fwd6Params
    .private_segment_fixed_size: 0
    .sgpr_count:     106
    .sgpr_spill_count: 165
    .symbol:         _Z5k_fwd6Params.kd
    .uniform_work_group_size: 1
    .uses_dynamic_stack: false
    .vgpr_count:     256
    .vgpr_spill_count: 0
    .wavefront_size: 64
